# GEMM K-loops: priority toggles and the duplicate LDS wait after each phase barrier removed (20 fewer instructions per K-iteration)
# baseline (speedup 1.0000x reference)
; #define PG8_STAGE(bufoff, gbase, voff) do { _Pragma("unroll") for (int _i = 0; _i < 2; ++_i) \
;         __builtin_amdgcn_global_load_lds((const unsigned*)((const char*)(gbase) + (voff)[_i]), (LAS unsigned*)(lds + (bufoff) + ldsw + _i * 8192), 16, 0, 0); } while (0)
; #define PG8_LDA(dst, b, h) do { _Pragma("unroll") for (int m = 0; m < 4; ++m) _Pragma("unroll") for (int k = 0; k < 2; ++k) dst[m][k] = *(const LAS bf16x8*)(lds + PG8_SA(b, h) + aoff + m * 2048 + k * 1024); } while (0)
; #define PG8_LDB(dst, b, h) do { _Pragma("unroll") for (int n = 0; n < 2; ++n) _Pragma("unroll") for (int k = 0; k < 2; ++k) dst[n][k] = *(const LAS bf16x8*)(lds + PG8_SB(b, h) + boff + n * 2048 + k * 1024); } while (0)
; #define PG8_MMA(ai, bj, At, Bt) do { __builtin_amdgcn_s_setprio(1); _Pragma("unroll") for (int m = 0; m < 4; ++m) _Pragma("unroll") for (int n = 0; n < 2; ++n) _Pragma("unroll") for (int k = 0; k < 2; ++k) \
;         acc[ai][bj][m][n] = __builtin_amdgcn_mfma_f32_16x16x32_bf16(Bt[n][k], At[m][k], acc[ai][bj][m][n], 0, 0, 0); __builtin_amdgcn_s_setprio(0); } while (0)
; #define PG8_WAIT_V(n) asm volatile("s_waitcnt vmcnt(" #n ")" ::: "memory")
; #define PG8_WAIT_L(n) asm volatile("s_waitcnt lgkmcnt(" #n ")" ::: "memory")
; #define PG8_BAR __builtin_amdgcn_s_barrier()
; #define PG8_SCHED __builtin_amdgcn_sched_barrier(0)
; template <class Epi>
; __device__ __forceinline__ void gemm_phase(LAS unsigned char* lds, const Gemm g, const StaticOrder& S, const Epi& E, const int wid) {
;     ...
;             const bool last = (t == nt - 2);
;             const char* a1 = cA + (size_t)(t + 1) * kstep;
;             const char* a2 = last ? nA : cA + (size_t)(t + 2) * kstep; const char* b2 = last ? nB : cB + (size_t)(t + 2) * kstep;
;             const char* a3 = a2 + kstep; const char* b3 = b2 + kstep;
;             PG8_LDB(B0, 0, 0); PG8_LDB(B1, 0, 1); PG8_SCHED; PG8_LDA(At, 0, 0); PG8_STAGE(PG8_SA(1, 1), a1 + hstepA, voffA);
;             PG8_WAIT_V(8); PG8_WAIT_L(0); PG8_BAR; PG8_MMA(0, 0, At, B0); PG8_MMA(0, 1, At, B1); PG8_BAR; PG8_SCHED;
;             PG8_LDA(At, 0, 1); PG8_STAGE(PG8_SB(0, 0), b2, voffB); PG8_STAGE(PG8_SB(0, 1), b2 + hstepB, voffB); PG8_STAGE(PG8_SA(0, 0), a2, voffA);
;             PG8_WAIT_V(8); PG8_WAIT_L(0); PG8_BAR; PG8_MMA(1, 0, At, B0); PG8_MMA(1, 1, At, B1); PG8_BAR; PG8_SCHED;
.LBB0_157:
	ds_read_b128 v[150:153], v157
	ds_read_b128 v[160:163], v157 offset:1024
	ds_read_b128 v[164:167], v157 offset:2048
	ds_read_b128 v[168:171], v157 offset:3072
	ds_read_b128 v[172:175], v158
	ds_read_b128 v[176:179], v158 offset:1024
	ds_read_b128 v[180:183], v158 offset:2048
	ds_read_b128 v[184:187], v158 offset:3072
	s_add_u32 s8, s10, 0x100
	s_addc_u32 s9, s11, 0
	s_cmp_eq_u32 s60, 28
	s_cselect_b32 s59, s51, s9
	s_cselect_b32 s58, s50, s8
	s_cselect_b32 s57, s20, s55
	s_cselect_b32 s56, s21, s49
	s_add_i32 m0, s0, 0xc000
	ds_read_b128 v[188:191], v159
	global_load_lds_dwordx4 v142, s[10:11]
	s_add_i32 m0, s0, 0xe000
	ds_read_b128 v[192:195], v159 offset:1024
	global_load_lds_dwordx4 v144, s[10:11]
	ds_read_b128 v[196:199], v159 offset:2048
	ds_read_b128 v[200:203], v159 offset:3072
	ds_read_b128 v[204:207], v159 offset:4096
	ds_read_b128 v[208:211], v159 offset:5120
	ds_read_b128 v[212:215], v159 offset:6144
	ds_read_b128 v[216:219], v159 offset:7168
	s_waitcnt vmcnt(8)
	s_waitcnt lgkmcnt(0)
	s_barrier
	v_mfma_f32_16x16x32_bf16 v[124:127], v[150:153], v[188:191], v[124:127]
	v_mfma_f32_16x16x32_bf16 v[120:123], v[164:167], v[188:191], v[120:123]
	v_mfma_f32_16x16x32_bf16 v[116:119], v[150:153], v[196:199], v[116:119]
	v_mfma_f32_16x16x32_bf16 v[112:115], v[164:167], v[196:199], v[112:115]
	v_mfma_f32_16x16x32_bf16 v[108:111], v[150:153], v[204:207], v[108:111]
	v_mfma_f32_16x16x32_bf16 v[104:107], v[164:167], v[204:207], v[104:107]
	v_mfma_f32_16x16x32_bf16 v[100:103], v[150:153], v[212:215], v[100:103]
	v_mfma_f32_16x16x32_bf16 v[96:99], v[164:167], v[212:215], v[96:99]
	v_mfma_f32_16x16x32_bf16 v[124:127], v[160:163], v[192:195], v[124:127]
	v_mfma_f32_16x16x32_bf16 v[120:123], v[168:171], v[192:195], v[120:123]
	v_mfma_f32_16x16x32_bf16 v[116:119], v[160:163], v[200:203], v[116:119]
	v_mfma_f32_16x16x32_bf16 v[112:115], v[168:171], v[200:203], v[112:115]
	v_mfma_f32_16x16x32_bf16 v[108:111], v[160:163], v[208:211], v[108:111]
	v_mfma_f32_16x16x32_bf16 v[104:107], v[168:171], v[208:211], v[104:107]
	v_mfma_f32_16x16x32_bf16 v[100:103], v[160:163], v[216:219], v[100:103]
	v_mfma_f32_16x16x32_bf16 v[96:99], v[168:171], v[216:219], v[96:99]
	v_mfma_f32_16x16x32_bf16 v[60:63], v[172:175], v[188:191], v[60:63]
	v_mfma_f32_16x16x32_bf16 v[56:59], v[180:183], v[188:191], v[56:59]
	v_mfma_f32_16x16x32_bf16 v[52:55], v[172:175], v[196:199], v[52:55]
	v_mfma_f32_16x16x32_bf16 v[48:51], v[180:183], v[196:199], v[48:51]
	v_mfma_f32_16x16x32_bf16 v[44:47], v[172:175], v[204:207], v[44:47]
	v_mfma_f32_16x16x32_bf16 v[40:43], v[180:183], v[204:207], v[40:43]
	v_mfma_f32_16x16x32_bf16 v[36:39], v[172:175], v[212:215], v[36:39]
	v_mfma_f32_16x16x32_bf16 v[32:35], v[180:183], v[212:215], v[32:35]
	v_mfma_f32_16x16x32_bf16 v[60:63], v[176:179], v[192:195], v[60:63]
	v_mfma_f32_16x16x32_bf16 v[56:59], v[184:187], v[192:195], v[56:59]
	v_mfma_f32_16x16x32_bf16 v[52:55], v[176:179], v[200:203], v[52:55]
	v_mfma_f32_16x16x32_bf16 v[48:51], v[184:187], v[200:203], v[48:51]
	v_mfma_f32_16x16x32_bf16 v[44:47], v[176:179], v[208:211], v[44:47]
	v_mfma_f32_16x16x32_bf16 v[40:43], v[184:187], v[208:211], v[40:43]
	v_mfma_f32_16x16x32_bf16 v[36:39], v[176:179], v[216:219], v[36:39]
	v_mfma_f32_16x16x32_bf16 v[32:35], v[184:187], v[216:219], v[32:35]
	s_barrier
	s_add_i32 s10, s68, s94
	s_mov_b32 m0, s10
	ds_read_b128 v[188:191], v159 offset:16384
	global_load_lds_dwordx4 v130, s[56:57]
	s_add_i32 m0, s10, 0x2000
	s_add_u32 s10, s56, 0x80000
	s_addc_u32 s11, s57, 0
	s_add_i32 s24, s69, s94
	global_load_lds_dwordx4 v134, s[56:57]
	s_mov_b32 m0, s24
	ds_read_b128 v[192:195], v159 offset:17408
	global_load_lds_dwordx4 v130, s[10:11]
	s_add_i32 m0, s24, 0x2000
	ds_read_b128 v[196:199], v159 offset:18432
	global_load_lds_dwordx4 v134, s[10:11]
	s_mov_b32 m0, s0
	ds_read_b128 v[200:203], v159 offset:19456
	global_load_lds_dwordx4 v128, s[58:59]
	s_mov_b32 m0, s1
	ds_read_b128 v[204:207], v159 offset:20480
	global_load_lds_dwordx4 v132, s[58:59]
	ds_read_b128 v[208:211], v159 offset:21504
	ds_read_b128 v[212:215], v159 offset:22528
	ds_read_b128 v[216:219], v159 offset:23552
	s_waitcnt vmcnt(8)
	s_waitcnt lgkmcnt(0)
	s_barrier
	v_mfma_f32_16x16x32_bf16 v[92:95], v[150:153], v[188:191], v[92:95]
	v_mfma_f32_16x16x32_bf16 v[88:91], v[164:167], v[188:191], v[88:91]
	v_mfma_f32_16x16x32_bf16 v[84:87], v[150:153], v[196:199], v[84:87]
	v_mfma_f32_16x16x32_bf16 v[80:83], v[164:167], v[196:199], v[80:83]
	v_mfma_f32_16x16x32_bf16 v[76:79], v[150:153], v[204:207], v[76:79]
	v_mfma_f32_16x16x32_bf16 v[72:75], v[164:167], v[204:207], v[72:75]
	v_mfma_f32_16x16x32_bf16 v[68:71], v[150:153], v[212:215], v[68:71]
	v_mfma_f32_16x16x32_bf16 v[64:67], v[164:167], v[212:215], v[64:67]
	v_mfma_f32_16x16x32_bf16 v[92:95], v[160:163], v[192:195], v[92:95]
	v_mfma_f32_16x16x32_bf16 v[88:91], v[168:171], v[192:195], v[88:91]
	v_mfma_f32_16x16x32_bf16 v[84:87], v[160:163], v[200:203], v[84:87]
	v_mfma_f32_16x16x32_bf16 v[80:83], v[168:171], v[200:203], v[80:83]
	v_mfma_f32_16x16x32_bf16 v[76:79], v[160:163], v[208:211], v[76:79]
	v_mfma_f32_16x16x32_bf16 v[72:75], v[168:171], v[208:211], v[72:75]
	v_mfma_f32_16x16x32_bf16 v[68:71], v[160:163], v[216:219], v[68:71]
	v_mfma_f32_16x16x32_bf16 v[64:67], v[168:171], v[216:219], v[64:67]
	v_mfma_f32_16x16x32_bf16 v[28:31], v[172:175], v[188:191], v[28:31]
	v_mfma_f32_16x16x32_bf16 v[24:27], v[180:183], v[188:191], v[24:27]
	v_mfma_f32_16x16x32_bf16 v[20:23], v[172:175], v[196:199], v[20:23]
	v_mfma_f32_16x16x32_bf16 v[16:19], v[180:183], v[196:199], v[16:19]
	v_mfma_f32_16x16x32_bf16 v[12:15], v[172:175], v[204:207], v[12:15]
	v_mfma_f32_16x16x32_bf16 v[8:11], v[180:183], v[204:207], v[8:11]
	v_mfma_f32_16x16x32_bf16 v[4:7], v[172:175], v[212:215], v[4:7]
	v_mfma_f32_16x16x32_bf16 v[0:3], v[180:183], v[212:215], v[0:3]
	v_mfma_f32_16x16x32_bf16 v[28:31], v[176:179], v[192:195], v[28:31]
	v_mfma_f32_16x16x32_bf16 v[24:27], v[184:187], v[192:195], v[24:27]
	v_mfma_f32_16x16x32_bf16 v[20:23], v[176:179], v[200:203], v[20:23]
	v_mfma_f32_16x16x32_bf16 v[16:19], v[184:187], v[200:203], v[16:19]
	v_mfma_f32_16x16x32_bf16 v[12:15], v[176:179], v[208:211], v[12:15]
	v_mfma_f32_16x16x32_bf16 v[8:11], v[184:187], v[208:211], v[8:11]
	v_mfma_f32_16x16x32_bf16 v[4:7], v[176:179], v[216:219], v[4:7]
	v_mfma_f32_16x16x32_bf16 v[0:3], v[184:187], v[216:219], v[0:3]
	s_barrier
; #define PG8_STAGE(bufoff, gbase, voff) do { _Pragma("unroll") for (int _i = 0; _i < 2; ++_i) \
;         __builtin_amdgcn_global_load_lds((const unsigned*)((const char*)(gbase) + (voff)[_i]), (LAS unsigned*)(lds + (bufoff) + ldsw + _i * 8192), 16, 0, 0); } while (0)
; #define PG8_LDA(dst, b, h) do { _Pragma("unroll") for (int m = 0; m < 4; ++m) _Pragma("unroll") for (int k = 0; k < 2; ++k) dst[m][k] = *(const LAS bf16x8*)(lds + PG8_SA(b, h) + aoff + m * 2048 + k * 1024); } while (0)
; #define PG8_LDB(dst, b, h) do { _Pragma("unroll") for (int n = 0; n < 2; ++n) _Pragma("unroll") for (int k = 0; k < 2; ++k) dst[n][k] = *(const LAS bf16x8*)(lds + PG8_SB(b, h) + boff + n * 2048 + k * 1024); } while (0)
; #define PG8_MMA(ai, bj, At, Bt) do { __builtin_amdgcn_s_setprio(1); _Pragma("unroll") for (int m = 0; m < 4; ++m) _Pragma("unroll") for (int n = 0; n < 2; ++n) _Pragma("unroll") for (int k = 0; k < 2; ++k) \
;         acc[ai][bj][m][n] = __builtin_amdgcn_mfma_f32_16x16x32_bf16(Bt[n][k], At[m][k], acc[ai][bj][m][n], 0, 0, 0); __builtin_amdgcn_s_setprio(0); } while (0)
; #define PG8_WAIT_V(n) asm volatile("s_waitcnt vmcnt(" #n ")" ::: "memory")
; #define PG8_WAIT_L(n) asm volatile("s_waitcnt lgkmcnt(" #n ")" ::: "memory")
; #define PG8_BAR __builtin_amdgcn_s_barrier()
; #define PG8_SCHED __builtin_amdgcn_sched_barrier(0)
; template <class Epi>
; __device__ __forceinline__ void gemm_phase(LAS unsigned char* lds, const Gemm g, const StaticOrder& S, const Epi& E, const int wid) {
;     ...
;             PG8_LDB(B0, 1, 0); PG8_LDB(B1, 1, 1); PG8_SCHED; PG8_LDA(At, 1, 0); PG8_STAGE(PG8_SA(0, 1), a2 + hstepA, voffA);
;             PG8_WAIT_V(8); PG8_WAIT_L(0); PG8_BAR; PG8_MMA(0, 0, At, B0); PG8_MMA(0, 1, At, B1); PG8_BAR; PG8_SCHED;
;             PG8_LDA(At, 1, 1); PG8_STAGE(PG8_SB(1, 0), b3, voffB); PG8_STAGE(PG8_SB(1, 1), b3 + hstepB, voffB); PG8_STAGE(PG8_SA(1, 0), a3, voffA);
;             PG8_WAIT_V(8); PG8_WAIT_L(0); PG8_BAR; PG8_MMA(1, 0, At, B0); PG8_MMA(1, 1, At, B1); PG8_BAR; PG8_SCHED;
;         }
;         if (wr == 0) PG8_BAR;
	s_add_i32 s24, 0, 0x18000
	v_add_u32_e32 v136, s24, v139
	s_add_i32 s25, 0, 0x1c000
	ds_read_b128 v[150:153], v136
	ds_read_b128 v[160:163], v136 offset:1024
	ds_read_b128 v[164:167], v136 offset:2048
	ds_read_b128 v[168:171], v136 offset:3072
	v_add_u32_e32 v136, s25, v139
	ds_read_b128 v[172:175], v136
	ds_read_b128 v[176:179], v136 offset:1024
	ds_read_b128 v[180:183], v136 offset:2048
	ds_read_b128 v[184:187], v136 offset:3072
	s_add_u32 s10, s58, 0x80000
	s_addc_u32 s11, s59, 0
	s_mov_b32 m0, s15
	ds_read_b128 v[188:191], v159 offset:32768
	global_load_lds_dwordx4 v128, s[10:11]
	s_mov_b32 m0, s26
	ds_read_b128 v[192:195], v159 offset:33792
	global_load_lds_dwordx4 v132, s[10:11]
	ds_read_b128 v[196:199], v159 offset:34816
	ds_read_b128 v[200:203], v159 offset:35840
	ds_read_b128 v[204:207], v159 offset:36864
	ds_read_b128 v[208:211], v159 offset:37888
	ds_read_b128 v[212:215], v159 offset:38912
	ds_read_b128 v[216:219], v159 offset:39936
	s_waitcnt vmcnt(8)
	s_waitcnt lgkmcnt(0)
	s_barrier
	v_mfma_f32_16x16x32_bf16 v[124:127], v[150:153], v[188:191], v[124:127]
	v_mfma_f32_16x16x32_bf16 v[120:123], v[164:167], v[188:191], v[120:123]
	v_mfma_f32_16x16x32_bf16 v[116:119], v[150:153], v[196:199], v[116:119]
	v_mfma_f32_16x16x32_bf16 v[112:115], v[164:167], v[196:199], v[112:115]
	v_mfma_f32_16x16x32_bf16 v[108:111], v[150:153], v[204:207], v[108:111]
	v_mfma_f32_16x16x32_bf16 v[104:107], v[164:167], v[204:207], v[104:107]
	v_mfma_f32_16x16x32_bf16 v[100:103], v[150:153], v[212:215], v[100:103]
	v_mfma_f32_16x16x32_bf16 v[96:99], v[164:167], v[212:215], v[96:99]
	v_mfma_f32_16x16x32_bf16 v[124:127], v[160:163], v[192:195], v[124:127]
	v_mfma_f32_16x16x32_bf16 v[120:123], v[168:171], v[192:195], v[120:123]
	v_mfma_f32_16x16x32_bf16 v[116:119], v[160:163], v[200:203], v[116:119]
	v_mfma_f32_16x16x32_bf16 v[112:115], v[168:171], v[200:203], v[112:115]
	v_mfma_f32_16x16x32_bf16 v[108:111], v[160:163], v[208:211], v[108:111]
	v_mfma_f32_16x16x32_bf16 v[104:107], v[168:171], v[208:211], v[104:107]
	v_mfma_f32_16x16x32_bf16 v[100:103], v[160:163], v[216:219], v[100:103]
	v_mfma_f32_16x16x32_bf16 v[96:99], v[168:171], v[216:219], v[96:99]
	v_mfma_f32_16x16x32_bf16 v[60:63], v[172:175], v[188:191], v[60:63]
	v_mfma_f32_16x16x32_bf16 v[56:59], v[180:183], v[188:191], v[56:59]
	v_mfma_f32_16x16x32_bf16 v[52:55], v[172:175], v[196:199], v[52:55]
	v_mfma_f32_16x16x32_bf16 v[48:51], v[180:183], v[196:199], v[48:51]
	v_mfma_f32_16x16x32_bf16 v[44:47], v[172:175], v[204:207], v[44:47]
	v_mfma_f32_16x16x32_bf16 v[40:43], v[180:183], v[204:207], v[40:43]
	v_mfma_f32_16x16x32_bf16 v[36:39], v[172:175], v[212:215], v[36:39]
	v_mfma_f32_16x16x32_bf16 v[32:35], v[180:183], v[212:215], v[32:35]
	v_mfma_f32_16x16x32_bf16 v[60:63], v[176:179], v[192:195], v[60:63]
	v_mfma_f32_16x16x32_bf16 v[56:59], v[184:187], v[192:195], v[56:59]
	v_mfma_f32_16x16x32_bf16 v[52:55], v[176:179], v[200:203], v[52:55]
	v_mfma_f32_16x16x32_bf16 v[48:51], v[184:187], v[200:203], v[48:51]
	v_mfma_f32_16x16x32_bf16 v[44:47], v[176:179], v[208:211], v[44:47]
	v_mfma_f32_16x16x32_bf16 v[40:43], v[184:187], v[208:211], v[40:43]
	v_mfma_f32_16x16x32_bf16 v[36:39], v[176:179], v[216:219], v[36:39]
	v_mfma_f32_16x16x32_bf16 v[32:35], v[184:187], v[216:219], v[32:35]
	s_barrier
	s_add_i32 s10, s24, s94
	s_add_u32 s98, s56, 0x80
	s_addc_u32 s99, s57, 0
	s_mov_b32 m0, s10
	ds_read_b128 v[188:191], v159 offset:49152
	global_load_lds_dwordx4 v130, s[98:99]
	s_add_i32 m0, s10, 0x2000
	s_add_u32 s10, s56, 0x80080
	s_addc_u32 s11, s57, 0
	s_add_i32 s24, s25, s94
	global_load_lds_dwordx4 v134, s[98:99]
	s_mov_b32 m0, s24
	ds_read_b128 v[192:195], v159 offset:50176
	global_load_lds_dwordx4 v130, s[10:11]
	s_add_i32 m0, s24, 0x2000
	ds_read_b128 v[196:199], v159 offset:51200
	global_load_lds_dwordx4 v134, s[10:11]
	s_add_u32 s100, s58, 0x80
	s_addc_u32 s101, s59, 0
	s_mov_b32 m0, s66
	ds_read_b128 v[200:203], v159 offset:52224
	global_load_lds_dwordx4 v128, s[100:101]
	s_mov_b32 m0, s67
	ds_read_b128 v[204:207], v159 offset:53248
	global_load_lds_dwordx4 v132, s[100:101]
	ds_read_b128 v[208:211], v159 offset:54272
	ds_read_b128 v[212:215], v159 offset:55296
	ds_read_b128 v[216:219], v159 offset:56320
	s_waitcnt vmcnt(8)
	s_waitcnt lgkmcnt(0)
	s_barrier
	v_mfma_f32_16x16x32_bf16 v[92:95], v[150:153], v[188:191], v[92:95]
	v_mfma_f32_16x16x32_bf16 v[88:91], v[164:167], v[188:191], v[88:91]
	v_mfma_f32_16x16x32_bf16 v[84:87], v[150:153], v[196:199], v[84:87]
	v_mfma_f32_16x16x32_bf16 v[80:83], v[164:167], v[196:199], v[80:83]
	v_mfma_f32_16x16x32_bf16 v[76:79], v[150:153], v[204:207], v[76:79]
	v_mfma_f32_16x16x32_bf16 v[72:75], v[164:167], v[204:207], v[72:75]
	v_mfma_f32_16x16x32_bf16 v[68:71], v[150:153], v[212:215], v[68:71]
	v_mfma_f32_16x16x32_bf16 v[64:67], v[164:167], v[212:215], v[64:67]
	v_mfma_f32_16x16x32_bf16 v[92:95], v[160:163], v[192:195], v[92:95]
	v_mfma_f32_16x16x32_bf16 v[88:91], v[168:171], v[192:195], v[88:91]
	v_mfma_f32_16x16x32_bf16 v[84:87], v[160:163], v[200:203], v[84:87]
	v_mfma_f32_16x16x32_bf16 v[80:83], v[168:171], v[200:203], v[80:83]
	v_mfma_f32_16x16x32_bf16 v[76:79], v[160:163], v[208:211], v[76:79]
	v_mfma_f32_16x16x32_bf16 v[72:75], v[168:171], v[208:211], v[72:75]
	v_mfma_f32_16x16x32_bf16 v[68:71], v[160:163], v[216:219], v[68:71]
	v_mfma_f32_16x16x32_bf16 v[64:67], v[168:171], v[216:219], v[64:67]
	v_mfma_f32_16x16x32_bf16 v[28:31], v[172:175], v[188:191], v[28:31]
	v_mfma_f32_16x16x32_bf16 v[24:27], v[180:183], v[188:191], v[24:27]
	v_mfma_f32_16x16x32_bf16 v[20:23], v[172:175], v[196:199], v[20:23]
	v_mfma_f32_16x16x32_bf16 v[16:19], v[180:183], v[196:199], v[16:19]
	v_mfma_f32_16x16x32_bf16 v[12:15], v[172:175], v[204:207], v[12:15]
	v_mfma_f32_16x16x32_bf16 v[8:11], v[180:183], v[204:207], v[8:11]
	v_mfma_f32_16x16x32_bf16 v[4:7], v[172:175], v[212:215], v[4:7]
	v_mfma_f32_16x16x32_bf16 v[0:3], v[180:183], v[212:215], v[0:3]
	v_mfma_f32_16x16x32_bf16 v[28:31], v[176:179], v[192:195], v[28:31]
	v_mfma_f32_16x16x32_bf16 v[24:27], v[184:187], v[192:195], v[24:27]
	v_mfma_f32_16x16x32_bf16 v[20:23], v[176:179], v[200:203], v[20:23]
	v_mfma_f32_16x16x32_bf16 v[16:19], v[184:187], v[200:203], v[16:19]
	v_mfma_f32_16x16x32_bf16 v[12:15], v[176:179], v[208:211], v[12:15]
	v_mfma_f32_16x16x32_bf16 v[8:11], v[184:187], v[208:211], v[8:11]
	v_mfma_f32_16x16x32_bf16 v[4:7], v[176:179], v[216:219], v[4:7]
	v_mfma_f32_16x16x32_bf16 v[0:3], v[184:187], v[216:219], v[0:3]
	s_barrier
	s_add_i32 s60, s60, 2
	s_add_u32 s49, s49, 0x100
	s_addc_u32 s55, s55, 0
	s_cmp_gt_u32 s60, 29
	s_mov_b64 s[10:11], s[8:9]
	s_cbranch_scc0 .LBB0_157
	s_and_b64 vcc, exec, s[22:23]
	s_cbranch_vccz .LBB0_160
	s_barrier

; #define PG8_STAGE(bufoff, gbase, voff) do { _Pragma("unroll") for (int _i = 0; _i < 2; ++_i) \
;         __builtin_amdgcn_global_load_lds((const unsigned*)((const char*)(gbase) + (voff)[_i]), (LAS unsigned*)(lds + (bufoff) + ldsw + _i * 8192), 16, 0, 0); } while (0)
; #define PG8_LDA(dst, b, h) do { _Pragma("unroll") for (int m = 0; m < 4; ++m) _Pragma("unroll") for (int k = 0; k < 2; ++k) dst[m][k] = *(const LAS bf16x8*)(lds + PG8_SA(b, h) + aoff + m * 2048 + k * 1024); } while (0)
; #define PG8_LDB(dst, b, h) do { _Pragma("unroll") for (int n = 0; n < 2; ++n) _Pragma("unroll") for (int k = 0; k < 2; ++k) dst[n][k] = *(const LAS bf16x8*)(lds + PG8_SB(b, h) + boff + n * 2048 + k * 1024); } while (0)
; #define PG8_MMA(ai, bj, At, Bt) do { __builtin_amdgcn_s_setprio(1); _Pragma("unroll") for (int m = 0; m < 4; ++m) _Pragma("unroll") for (int n = 0; n < 2; ++n) _Pragma("unroll") for (int k = 0; k < 2; ++k) \
;         acc[ai][bj][m][n] = __builtin_amdgcn_mfma_f32_16x16x32_bf16(Bt[n][k], At[m][k], acc[ai][bj][m][n], 0, 0, 0); __builtin_amdgcn_s_setprio(0); } while (0)
; #define PG8_WAIT_V(n) asm volatile("s_waitcnt vmcnt(" #n ")" ::: "memory")
; #define PG8_WAIT_L(n) asm volatile("s_waitcnt lgkmcnt(" #n ")" ::: "memory")
; #define PG8_BAR __builtin_amdgcn_s_barrier()
; #define PG8_SCHED __builtin_amdgcn_sched_barrier(0)
; template <class Epi>
; __device__ __forceinline__ void gemm_phase(LAS unsigned char* lds, const Gemm g, const StaticOrder& S, const Epi& E, const int wid) {
;     ...
;             const bool last = (t == nt - 2);
;             const char* a1 = cA + (size_t)(t + 1) * kstep;
;             const char* a2 = last ? nA : cA + (size_t)(t + 2) * kstep; const char* b2 = last ? nB : cB + (size_t)(t + 2) * kstep;
;             const char* a3 = a2 + kstep; const char* b3 = b2 + kstep;
;             PG8_LDB(B0, 0, 0); PG8_LDB(B1, 0, 1); PG8_SCHED; PG8_LDA(At, 0, 0); PG8_STAGE(PG8_SA(1, 1), a1 + hstepA, voffA);
;             PG8_WAIT_V(8); PG8_WAIT_L(0); PG8_BAR; PG8_MMA(0, 0, At, B0); PG8_MMA(0, 1, At, B1); PG8_BAR; PG8_SCHED;
;             PG8_LDA(At, 0, 1); PG8_STAGE(PG8_SB(0, 0), b2, voffB); PG8_STAGE(PG8_SB(0, 1), b2 + hstepB, voffB); PG8_STAGE(PG8_SA(0, 0), a2, voffA);
;             PG8_WAIT_V(8); PG8_WAIT_L(0); PG8_BAR; PG8_MMA(1, 0, At, B0); PG8_MMA(1, 1, At, B1); PG8_BAR; PG8_SCHED;
.LBB0_1669:
	ds_read_b128 v[144:147], v157
	ds_read_b128 v[148:151], v157 offset:1024
	ds_read_b128 v[160:163], v157 offset:2048
	ds_read_b128 v[164:167], v157 offset:3072
	ds_read_b128 v[168:171], v158
	ds_read_b128 v[172:175], v158 offset:1024
	ds_read_b128 v[176:179], v158 offset:2048
	ds_read_b128 v[180:183], v158 offset:3072
	s_add_u32 s6, s46, 0x100
	s_addc_u32 s7, s47, 0
	s_cmp_eq_u32 s55, 12
	s_cselect_b32 s51, s43, s7
	s_cselect_b32 s50, s42, s6
	s_cselect_b32 s49, s11, s54
	s_cselect_b32 s48, s21, s53
	s_add_i32 m0, s0, 0xc000
	ds_read_b128 v[184:187], v159
	global_load_lds_dwordx4 v136, s[46:47]
	s_add_i32 m0, s0, 0xe000
	ds_read_b128 v[188:191], v159 offset:1024
	global_load_lds_dwordx4 v138, s[46:47]
	ds_read_b128 v[192:195], v159 offset:2048
	ds_read_b128 v[196:199], v159 offset:3072
	ds_read_b128 v[200:203], v159 offset:4096
	ds_read_b128 v[204:207], v159 offset:5120
	ds_read_b128 v[208:211], v159 offset:6144
	ds_read_b128 v[212:215], v159 offset:7168
	s_waitcnt vmcnt(8)
	s_waitcnt lgkmcnt(0)
	s_barrier
	v_mfma_f32_16x16x32_bf16 v[124:127], v[144:147], v[184:187], v[124:127]
	v_mfma_f32_16x16x32_bf16 v[120:123], v[160:163], v[184:187], v[120:123]
	v_mfma_f32_16x16x32_bf16 v[116:119], v[144:147], v[192:195], v[116:119]
	v_mfma_f32_16x16x32_bf16 v[112:115], v[160:163], v[192:195], v[112:115]
	v_mfma_f32_16x16x32_bf16 v[108:111], v[144:147], v[200:203], v[108:111]
	v_mfma_f32_16x16x32_bf16 v[104:107], v[160:163], v[200:203], v[104:107]
	v_mfma_f32_16x16x32_bf16 v[100:103], v[144:147], v[208:211], v[100:103]
	v_mfma_f32_16x16x32_bf16 v[96:99], v[160:163], v[208:211], v[96:99]
	v_mfma_f32_16x16x32_bf16 v[124:127], v[148:151], v[188:191], v[124:127]
	v_mfma_f32_16x16x32_bf16 v[120:123], v[164:167], v[188:191], v[120:123]
	v_mfma_f32_16x16x32_bf16 v[116:119], v[148:151], v[196:199], v[116:119]
	v_mfma_f32_16x16x32_bf16 v[112:115], v[164:167], v[196:199], v[112:115]
	v_mfma_f32_16x16x32_bf16 v[108:111], v[148:151], v[204:207], v[108:111]
	v_mfma_f32_16x16x32_bf16 v[104:107], v[164:167], v[204:207], v[104:107]
	v_mfma_f32_16x16x32_bf16 v[100:103], v[148:151], v[212:215], v[100:103]
	v_mfma_f32_16x16x32_bf16 v[96:99], v[164:167], v[212:215], v[96:99]
	v_mfma_f32_16x16x32_bf16 v[68:71], v[168:171], v[184:187], v[68:71]
	v_mfma_f32_16x16x32_bf16 v[60:63], v[176:179], v[184:187], v[60:63]
	v_mfma_f32_16x16x32_bf16 v[52:55], v[168:171], v[192:195], v[52:55]
	v_mfma_f32_16x16x32_bf16 v[48:51], v[176:179], v[192:195], v[48:51]
	v_mfma_f32_16x16x32_bf16 v[44:47], v[168:171], v[200:203], v[44:47]
	v_mfma_f32_16x16x32_bf16 v[40:43], v[176:179], v[200:203], v[40:43]
	v_mfma_f32_16x16x32_bf16 v[36:39], v[168:171], v[208:211], v[36:39]
	v_mfma_f32_16x16x32_bf16 v[32:35], v[176:179], v[208:211], v[32:35]
	v_mfma_f32_16x16x32_bf16 v[68:71], v[172:175], v[188:191], v[68:71]
	v_mfma_f32_16x16x32_bf16 v[60:63], v[180:183], v[188:191], v[60:63]
	v_mfma_f32_16x16x32_bf16 v[52:55], v[172:175], v[196:199], v[52:55]
	v_mfma_f32_16x16x32_bf16 v[48:51], v[180:183], v[196:199], v[48:51]
	v_mfma_f32_16x16x32_bf16 v[44:47], v[172:175], v[204:207], v[44:47]
	v_mfma_f32_16x16x32_bf16 v[40:43], v[180:183], v[204:207], v[40:43]
	v_mfma_f32_16x16x32_bf16 v[36:39], v[172:175], v[212:215], v[36:39]
	v_mfma_f32_16x16x32_bf16 v[32:35], v[180:183], v[212:215], v[32:35]
	s_barrier
	s_add_i32 s24, s36, s94
	s_mov_b32 m0, s24
	ds_read_b128 v[184:187], v159 offset:16384
	global_load_lds_dwordx4 v132, s[48:49]
	s_add_i32 m0, s24, 0x2000
	s_add_u32 s24, s48, 0x40000
	s_addc_u32 s25, s49, 0
	s_add_i32 s46, s37, s94
	global_load_lds_dwordx4 v128, s[48:49]
	s_mov_b32 m0, s46
	ds_read_b128 v[188:191], v159 offset:17408
	global_load_lds_dwordx4 v132, s[24:25]
	s_add_i32 m0, s46, 0x2000
	ds_read_b128 v[192:195], v159 offset:18432
	global_load_lds_dwordx4 v128, s[24:25]
	s_mov_b32 m0, s0
	ds_read_b128 v[196:199], v159 offset:19456
	global_load_lds_dwordx4 v134, s[50:51]
	s_mov_b32 m0, s1
	ds_read_b128 v[200:203], v159 offset:20480
	global_load_lds_dwordx4 v130, s[50:51]
	ds_read_b128 v[204:207], v159 offset:21504
	ds_read_b128 v[208:211], v159 offset:22528
	ds_read_b128 v[212:215], v159 offset:23552
	s_waitcnt vmcnt(8)
	s_waitcnt lgkmcnt(0)
	s_barrier
	v_mfma_f32_16x16x32_bf16 v[92:95], v[144:147], v[184:187], v[92:95]
	v_mfma_f32_16x16x32_bf16 v[88:91], v[160:163], v[184:187], v[88:91]
	v_mfma_f32_16x16x32_bf16 v[84:87], v[144:147], v[192:195], v[84:87]
	v_mfma_f32_16x16x32_bf16 v[80:83], v[160:163], v[192:195], v[80:83]
	v_mfma_f32_16x16x32_bf16 v[76:79], v[144:147], v[200:203], v[76:79]
	v_mfma_f32_16x16x32_bf16 v[72:75], v[160:163], v[200:203], v[72:75]
	v_mfma_f32_16x16x32_bf16 v[64:67], v[144:147], v[208:211], v[64:67]
	v_mfma_f32_16x16x32_bf16 v[56:59], v[160:163], v[208:211], v[56:59]
	v_mfma_f32_16x16x32_bf16 v[92:95], v[148:151], v[188:191], v[92:95]
	v_mfma_f32_16x16x32_bf16 v[88:91], v[164:167], v[188:191], v[88:91]
	v_mfma_f32_16x16x32_bf16 v[84:87], v[148:151], v[196:199], v[84:87]
	v_mfma_f32_16x16x32_bf16 v[80:83], v[164:167], v[196:199], v[80:83]
	v_mfma_f32_16x16x32_bf16 v[76:79], v[148:151], v[204:207], v[76:79]
	v_mfma_f32_16x16x32_bf16 v[72:75], v[164:167], v[204:207], v[72:75]
	v_mfma_f32_16x16x32_bf16 v[64:67], v[148:151], v[212:215], v[64:67]
	v_mfma_f32_16x16x32_bf16 v[56:59], v[164:167], v[212:215], v[56:59]
	v_mfma_f32_16x16x32_bf16 v[28:31], v[168:171], v[184:187], v[28:31]
	v_mfma_f32_16x16x32_bf16 v[24:27], v[176:179], v[184:187], v[24:27]
	v_mfma_f32_16x16x32_bf16 v[20:23], v[168:171], v[192:195], v[20:23]
	v_mfma_f32_16x16x32_bf16 v[16:19], v[176:179], v[192:195], v[16:19]
	v_mfma_f32_16x16x32_bf16 v[12:15], v[168:171], v[200:203], v[12:15]
	v_mfma_f32_16x16x32_bf16 v[8:11], v[176:179], v[200:203], v[8:11]
	v_mfma_f32_16x16x32_bf16 v[4:7], v[168:171], v[208:211], v[4:7]
	v_mfma_f32_16x16x32_bf16 v[0:3], v[176:179], v[208:211], v[0:3]
	v_mfma_f32_16x16x32_bf16 v[28:31], v[172:175], v[188:191], v[28:31]
	v_mfma_f32_16x16x32_bf16 v[24:27], v[180:183], v[188:191], v[24:27]
	v_mfma_f32_16x16x32_bf16 v[20:23], v[172:175], v[196:199], v[20:23]
	v_mfma_f32_16x16x32_bf16 v[16:19], v[180:183], v[196:199], v[16:19]
	v_mfma_f32_16x16x32_bf16 v[12:15], v[172:175], v[204:207], v[12:15]
	v_mfma_f32_16x16x32_bf16 v[8:11], v[180:183], v[204:207], v[8:11]
	v_mfma_f32_16x16x32_bf16 v[4:7], v[172:175], v[212:215], v[4:7]
	v_mfma_f32_16x16x32_bf16 v[0:3], v[180:183], v[212:215], v[0:3]
	s_barrier
; #define PG8_STAGE(bufoff, gbase, voff) do { _Pragma("unroll") for (int _i = 0; _i < 2; ++_i) \
;         __builtin_amdgcn_global_load_lds((const unsigned*)((const char*)(gbase) + (voff)[_i]), (LAS unsigned*)(lds + (bufoff) + ldsw + _i * 8192), 16, 0, 0); } while (0)
; #define PG8_LDA(dst, b, h) do { _Pragma("unroll") for (int m = 0; m < 4; ++m) _Pragma("unroll") for (int k = 0; k < 2; ++k) dst[m][k] = *(const LAS bf16x8*)(lds + PG8_SA(b, h) + aoff + m * 2048 + k * 1024); } while (0)
; #define PG8_LDB(dst, b, h) do { _Pragma("unroll") for (int n = 0; n < 2; ++n) _Pragma("unroll") for (int k = 0; k < 2; ++k) dst[n][k] = *(const LAS bf16x8*)(lds + PG8_SB(b, h) + boff + n * 2048 + k * 1024); } while (0)
; #define PG8_MMA(ai, bj, At, Bt) do { __builtin_amdgcn_s_setprio(1); _Pragma("unroll") for (int m = 0; m < 4; ++m) _Pragma("unroll") for (int n = 0; n < 2; ++n) _Pragma("unroll") for (int k = 0; k < 2; ++k) \
;         acc[ai][bj][m][n] = __builtin_amdgcn_mfma_f32_16x16x32_bf16(Bt[n][k], At[m][k], acc[ai][bj][m][n], 0, 0, 0); __builtin_amdgcn_s_setprio(0); } while (0)
; #define PG8_WAIT_V(n) asm volatile("s_waitcnt vmcnt(" #n ")" ::: "memory")
; #define PG8_WAIT_L(n) asm volatile("s_waitcnt lgkmcnt(" #n ")" ::: "memory")
; #define PG8_BAR __builtin_amdgcn_s_barrier()
; #define PG8_SCHED __builtin_amdgcn_sched_barrier(0)
; template <class Epi>
; __device__ __forceinline__ void gemm_phase(LAS unsigned char* lds, const Gemm g, const StaticOrder& S, const Epi& E, const int wid) {
;     ...
;             PG8_LDB(B0, 1, 0); PG8_LDB(B1, 1, 1); PG8_SCHED; PG8_LDA(At, 1, 0); PG8_STAGE(PG8_SA(0, 1), a2 + hstepA, voffA);
;             PG8_WAIT_V(8); PG8_WAIT_L(0); PG8_BAR; PG8_MMA(0, 0, At, B0); PG8_MMA(0, 1, At, B1); PG8_BAR; PG8_SCHED;
;             PG8_LDA(At, 1, 1); PG8_STAGE(PG8_SB(1, 0), b3, voffB); PG8_STAGE(PG8_SB(1, 1), b3 + hstepB, voffB); PG8_STAGE(PG8_SA(1, 0), a3, voffA);
;             PG8_WAIT_V(8); PG8_WAIT_L(0); PG8_BAR; PG8_MMA(1, 0, At, B0); PG8_MMA(1, 1, At, B1); PG8_BAR; PG8_SCHED;
;         }
;         if (wr == 0) PG8_BAR;
	s_add_i32 s46, 0, 0x18000
	s_add_i32 s47, 0, 0x1c000
	v_add_u32_e32 v164, s46, v154
	v_add_u32_e32 v180, s47, v154
	ds_read_b128 v[144:147], v164
	ds_read_b128 v[148:151], v164 offset:1024
	ds_read_b128 v[160:163], v164 offset:2048
	ds_read_b128 v[164:167], v164 offset:3072
	ds_read_b128 v[168:171], v180
	ds_read_b128 v[172:175], v180 offset:1024
	ds_read_b128 v[176:179], v180 offset:2048
	ds_read_b128 v[180:183], v180 offset:3072
	s_add_u32 s24, s50, 0x40000
	s_addc_u32 s25, s51, 0
	s_mov_b32 m0, s15
	ds_read_b128 v[184:187], v159 offset:32768
	global_load_lds_dwordx4 v134, s[24:25]
	s_mov_b32 m0, s26
	ds_read_b128 v[188:191], v159 offset:33792
	global_load_lds_dwordx4 v130, s[24:25]
	ds_read_b128 v[192:195], v159 offset:34816
	ds_read_b128 v[196:199], v159 offset:35840
	ds_read_b128 v[200:203], v159 offset:36864
	ds_read_b128 v[204:207], v159 offset:37888
	ds_read_b128 v[208:211], v159 offset:38912
	ds_read_b128 v[212:215], v159 offset:39936
	s_waitcnt vmcnt(8)
	s_waitcnt lgkmcnt(0)
	s_barrier
	v_mfma_f32_16x16x32_bf16 v[124:127], v[144:147], v[184:187], v[124:127]
	v_mfma_f32_16x16x32_bf16 v[120:123], v[160:163], v[184:187], v[120:123]
	v_mfma_f32_16x16x32_bf16 v[116:119], v[144:147], v[192:195], v[116:119]
	v_mfma_f32_16x16x32_bf16 v[112:115], v[160:163], v[192:195], v[112:115]
	v_mfma_f32_16x16x32_bf16 v[108:111], v[144:147], v[200:203], v[108:111]
	v_mfma_f32_16x16x32_bf16 v[104:107], v[160:163], v[200:203], v[104:107]
	v_mfma_f32_16x16x32_bf16 v[100:103], v[144:147], v[208:211], v[100:103]
	v_mfma_f32_16x16x32_bf16 v[96:99], v[160:163], v[208:211], v[96:99]
	v_mfma_f32_16x16x32_bf16 v[124:127], v[148:151], v[188:191], v[124:127]
	v_mfma_f32_16x16x32_bf16 v[120:123], v[164:167], v[188:191], v[120:123]
	v_mfma_f32_16x16x32_bf16 v[116:119], v[148:151], v[196:199], v[116:119]
	v_mfma_f32_16x16x32_bf16 v[112:115], v[164:167], v[196:199], v[112:115]
	v_mfma_f32_16x16x32_bf16 v[108:111], v[148:151], v[204:207], v[108:111]
	v_mfma_f32_16x16x32_bf16 v[104:107], v[164:167], v[204:207], v[104:107]
	v_mfma_f32_16x16x32_bf16 v[100:103], v[148:151], v[212:215], v[100:103]
	v_mfma_f32_16x16x32_bf16 v[96:99], v[164:167], v[212:215], v[96:99]
	v_mfma_f32_16x16x32_bf16 v[68:71], v[168:171], v[184:187], v[68:71]
	v_mfma_f32_16x16x32_bf16 v[60:63], v[176:179], v[184:187], v[60:63]
	v_mfma_f32_16x16x32_bf16 v[52:55], v[168:171], v[192:195], v[52:55]
	v_mfma_f32_16x16x32_bf16 v[48:51], v[176:179], v[192:195], v[48:51]
	v_mfma_f32_16x16x32_bf16 v[44:47], v[168:171], v[200:203], v[44:47]
	v_mfma_f32_16x16x32_bf16 v[40:43], v[176:179], v[200:203], v[40:43]
	v_mfma_f32_16x16x32_bf16 v[36:39], v[168:171], v[208:211], v[36:39]
	v_mfma_f32_16x16x32_bf16 v[32:35], v[176:179], v[208:211], v[32:35]
	v_mfma_f32_16x16x32_bf16 v[68:71], v[172:175], v[188:191], v[68:71]
	v_mfma_f32_16x16x32_bf16 v[60:63], v[180:183], v[188:191], v[60:63]
	v_mfma_f32_16x16x32_bf16 v[52:55], v[172:175], v[196:199], v[52:55]
	v_mfma_f32_16x16x32_bf16 v[48:51], v[180:183], v[196:199], v[48:51]
	v_mfma_f32_16x16x32_bf16 v[44:47], v[172:175], v[204:207], v[44:47]
	v_mfma_f32_16x16x32_bf16 v[40:43], v[180:183], v[204:207], v[40:43]
	v_mfma_f32_16x16x32_bf16 v[36:39], v[172:175], v[212:215], v[36:39]
	v_mfma_f32_16x16x32_bf16 v[32:35], v[180:183], v[212:215], v[32:35]
	s_barrier
	s_add_i32 s24, s46, s94
	s_add_u32 s98, s48, 0x80
	s_addc_u32 s99, s49, 0
	s_mov_b32 m0, s24
	ds_read_b128 v[184:187], v159 offset:49152
	global_load_lds_dwordx4 v132, s[98:99]
	s_add_i32 m0, s24, 0x2000
	s_add_u32 s24, s48, 0x40080
	s_addc_u32 s25, s49, 0
	s_add_i32 s46, s47, s94
	global_load_lds_dwordx4 v128, s[98:99]
	s_mov_b32 m0, s46
	ds_read_b128 v[188:191], v159 offset:50176
	global_load_lds_dwordx4 v132, s[24:25]
	s_add_i32 m0, s46, 0x2000
	ds_read_b128 v[192:195], v159 offset:51200
	global_load_lds_dwordx4 v128, s[24:25]
	s_add_u32 s100, s50, 0x80
	s_addc_u32 s101, s51, 0
	s_mov_b32 m0, s28
	ds_read_b128 v[196:199], v159 offset:52224
	global_load_lds_dwordx4 v134, s[100:101]
	s_mov_b32 m0, s29
	ds_read_b128 v[200:203], v159 offset:53248
	global_load_lds_dwordx4 v130, s[100:101]
	ds_read_b128 v[204:207], v159 offset:54272
	ds_read_b128 v[208:211], v159 offset:55296
	ds_read_b128 v[212:215], v159 offset:56320
	s_waitcnt vmcnt(8)
	s_waitcnt lgkmcnt(0)
	s_barrier
	v_mfma_f32_16x16x32_bf16 v[92:95], v[144:147], v[184:187], v[92:95]
	v_mfma_f32_16x16x32_bf16 v[88:91], v[160:163], v[184:187], v[88:91]
	v_mfma_f32_16x16x32_bf16 v[84:87], v[144:147], v[192:195], v[84:87]
	v_mfma_f32_16x16x32_bf16 v[80:83], v[160:163], v[192:195], v[80:83]
	v_mfma_f32_16x16x32_bf16 v[76:79], v[144:147], v[200:203], v[76:79]
	v_mfma_f32_16x16x32_bf16 v[72:75], v[160:163], v[200:203], v[72:75]
	v_mfma_f32_16x16x32_bf16 v[64:67], v[144:147], v[208:211], v[64:67]
	v_mfma_f32_16x16x32_bf16 v[56:59], v[160:163], v[208:211], v[56:59]
	v_mfma_f32_16x16x32_bf16 v[92:95], v[148:151], v[188:191], v[92:95]
	v_mfma_f32_16x16x32_bf16 v[88:91], v[164:167], v[188:191], v[88:91]
	v_mfma_f32_16x16x32_bf16 v[84:87], v[148:151], v[196:199], v[84:87]
	v_mfma_f32_16x16x32_bf16 v[80:83], v[164:167], v[196:199], v[80:83]
	v_mfma_f32_16x16x32_bf16 v[76:79], v[148:151], v[204:207], v[76:79]
	v_mfma_f32_16x16x32_bf16 v[72:75], v[164:167], v[204:207], v[72:75]
	v_mfma_f32_16x16x32_bf16 v[64:67], v[148:151], v[212:215], v[64:67]
	v_mfma_f32_16x16x32_bf16 v[56:59], v[164:167], v[212:215], v[56:59]
	v_mfma_f32_16x16x32_bf16 v[28:31], v[168:171], v[184:187], v[28:31]
	v_mfma_f32_16x16x32_bf16 v[24:27], v[176:179], v[184:187], v[24:27]
	v_mfma_f32_16x16x32_bf16 v[20:23], v[168:171], v[192:195], v[20:23]
	v_mfma_f32_16x16x32_bf16 v[16:19], v[176:179], v[192:195], v[16:19]
	v_mfma_f32_16x16x32_bf16 v[12:15], v[168:171], v[200:203], v[12:15]
	v_mfma_f32_16x16x32_bf16 v[8:11], v[176:179], v[200:203], v[8:11]
	v_mfma_f32_16x16x32_bf16 v[4:7], v[168:171], v[208:211], v[4:7]
	v_mfma_f32_16x16x32_bf16 v[0:3], v[176:179], v[208:211], v[0:3]
	v_mfma_f32_16x16x32_bf16 v[28:31], v[172:175], v[188:191], v[28:31]
	v_mfma_f32_16x16x32_bf16 v[24:27], v[180:183], v[188:191], v[24:27]
	v_mfma_f32_16x16x32_bf16 v[20:23], v[172:175], v[196:199], v[20:23]
	v_mfma_f32_16x16x32_bf16 v[16:19], v[180:183], v[196:199], v[16:19]
	v_mfma_f32_16x16x32_bf16 v[12:15], v[172:175], v[204:207], v[12:15]
	v_mfma_f32_16x16x32_bf16 v[8:11], v[180:183], v[204:207], v[8:11]
	v_mfma_f32_16x16x32_bf16 v[4:7], v[172:175], v[212:215], v[4:7]
	v_mfma_f32_16x16x32_bf16 v[0:3], v[180:183], v[212:215], v[0:3]
	s_barrier
	s_add_i32 s55, s55, 2
	s_add_u32 s53, s53, 0x100
	s_addc_u32 s54, s54, 0
	s_cmp_gt_u32 s55, 13
	s_mov_b64 s[46:47], s[6:7]
	s_cbranch_scc0 .LBB0_1669
	s_and_b64 vcc, exec, s[22:23]
	s_cbranch_vccz .LBB0_1672
	s_barrier

; #define PG8_STAGE(bufoff, gbase, voff) do { _Pragma("unroll") for (int _i = 0; _i < 2; ++_i) \
;         __builtin_amdgcn_global_load_lds((const unsigned*)((const char*)(gbase) + (voff)[_i]), (LAS unsigned*)(lds + (bufoff) + ldsw + _i * 8192), 16, 0, 0); } while (0)
; #define PG8_LDA(dst, b, h) do { _Pragma("unroll") for (int m = 0; m < 4; ++m) _Pragma("unroll") for (int k = 0; k < 2; ++k) dst[m][k] = *(const LAS bf16x8*)(lds + PG8_SA(b, h) + aoff + m * 2048 + k * 1024); } while (0)
; #define PG8_LDB(dst, b, h) do { _Pragma("unroll") for (int n = 0; n < 2; ++n) _Pragma("unroll") for (int k = 0; k < 2; ++k) dst[n][k] = *(const LAS bf16x8*)(lds + PG8_SB(b, h) + boff + n * 2048 + k * 1024); } while (0)
; #define PG8_MMA(ai, bj, At, Bt) do { __builtin_amdgcn_s_setprio(1); _Pragma("unroll") for (int m = 0; m < 4; ++m) _Pragma("unroll") for (int n = 0; n < 2; ++n) _Pragma("unroll") for (int k = 0; k < 2; ++k) \
;         acc[ai][bj][m][n] = __builtin_amdgcn_mfma_f32_16x16x32_bf16(Bt[n][k], At[m][k], acc[ai][bj][m][n], 0, 0, 0); __builtin_amdgcn_s_setprio(0); } while (0)
; #define PG8_WAIT_V(n) asm volatile("s_waitcnt vmcnt(" #n ")" ::: "memory")
; #define PG8_WAIT_L(n) asm volatile("s_waitcnt lgkmcnt(" #n ")" ::: "memory")
; #define PG8_BAR __builtin_amdgcn_s_barrier()
; #define PG8_SCHED __builtin_amdgcn_sched_barrier(0)
; template <class Epi>
; __device__ __forceinline__ void gemm_phase(LAS unsigned char* lds, const Gemm g, const StaticOrder& S, const Epi& E, const int wid) {
;     ...
;             const bool last = (t == nt - 2);
;             const char* a1 = cA + (size_t)(t + 1) * kstep;
;             const char* a2 = last ? nA : cA + (size_t)(t + 2) * kstep; const char* b2 = last ? nB : cB + (size_t)(t + 2) * kstep;
;             const char* a3 = a2 + kstep; const char* b3 = b2 + kstep;
;             PG8_LDB(B0, 0, 0); PG8_LDB(B1, 0, 1); PG8_SCHED; PG8_LDA(At, 0, 0); PG8_STAGE(PG8_SA(1, 1), a1 + hstepA, voffA);
;             PG8_WAIT_V(8); PG8_WAIT_L(0); PG8_BAR; PG8_MMA(0, 0, At, B0); PG8_MMA(0, 1, At, B1); PG8_BAR; PG8_SCHED;
;             PG8_LDA(At, 0, 1); PG8_STAGE(PG8_SB(0, 0), b2, voffB); PG8_STAGE(PG8_SB(0, 1), b2 + hstepB, voffB); PG8_STAGE(PG8_SA(0, 0), a2, voffA);
;             PG8_WAIT_V(8); PG8_WAIT_L(0); PG8_BAR; PG8_MMA(1, 0, At, B0); PG8_MMA(1, 1, At, B1); PG8_BAR; PG8_SCHED;
.LBB0_1692:
	ds_read_b128 v[144:147], v159
	ds_read_b128 v[148:151], v159 offset:1024
	ds_read_b128 v[152:155], v159 offset:2048
	ds_read_b128 v[162:165], v159 offset:3072
	ds_read_b128 v[166:169], v160
	ds_read_b128 v[170:173], v160 offset:1024
	ds_read_b128 v[174:177], v160 offset:2048
	ds_read_b128 v[178:181], v160 offset:3072
	s_add_u32 s6, s50, 0x100
	s_addc_u32 s7, s51, 0
	s_cmp_eq_u32 s58, 12
	s_cselect_b32 s55, s47, s7
	s_cselect_b32 s54, s46, s6
	s_cselect_b32 s53, s21, s57
	s_cselect_b32 s52, s38, s45
	s_add_i32 m0, s0, 0xc000
	ds_read_b128 v[182:185], v161
	global_load_lds_dwordx4 v136, s[50:51]
	s_add_i32 m0, s0, 0xe000
	ds_read_b128 v[186:189], v161 offset:1024
	global_load_lds_dwordx4 v138, s[50:51]
	ds_read_b128 v[190:193], v161 offset:2048
	ds_read_b128 v[194:197], v161 offset:3072
	ds_read_b128 v[198:201], v161 offset:4096
	ds_read_b128 v[202:205], v161 offset:5120
	ds_read_b128 v[206:209], v161 offset:6144
	ds_read_b128 v[210:213], v161 offset:7168
	s_waitcnt vmcnt(8)
	s_waitcnt lgkmcnt(0)
	s_barrier
	v_mfma_f32_16x16x32_bf16 v[124:127], v[144:147], v[182:185], v[124:127]
	v_mfma_f32_16x16x32_bf16 v[120:123], v[152:155], v[182:185], v[120:123]
	v_mfma_f32_16x16x32_bf16 v[116:119], v[144:147], v[190:193], v[116:119]
	v_mfma_f32_16x16x32_bf16 v[112:115], v[152:155], v[190:193], v[112:115]
	v_mfma_f32_16x16x32_bf16 v[108:111], v[144:147], v[198:201], v[108:111]
	v_mfma_f32_16x16x32_bf16 v[104:107], v[152:155], v[198:201], v[104:107]
	v_mfma_f32_16x16x32_bf16 v[100:103], v[144:147], v[206:209], v[100:103]
	v_mfma_f32_16x16x32_bf16 v[96:99], v[152:155], v[206:209], v[96:99]
	v_mfma_f32_16x16x32_bf16 v[124:127], v[148:151], v[186:189], v[124:127]
	v_mfma_f32_16x16x32_bf16 v[120:123], v[162:165], v[186:189], v[120:123]
	v_mfma_f32_16x16x32_bf16 v[116:119], v[148:151], v[194:197], v[116:119]
	v_mfma_f32_16x16x32_bf16 v[112:115], v[162:165], v[194:197], v[112:115]
	v_mfma_f32_16x16x32_bf16 v[108:111], v[148:151], v[202:205], v[108:111]
	v_mfma_f32_16x16x32_bf16 v[104:107], v[162:165], v[202:205], v[104:107]
	v_mfma_f32_16x16x32_bf16 v[100:103], v[148:151], v[210:213], v[100:103]
	v_mfma_f32_16x16x32_bf16 v[96:99], v[162:165], v[210:213], v[96:99]
	v_mfma_f32_16x16x32_bf16 v[60:63], v[166:169], v[182:185], v[60:63]
	v_mfma_f32_16x16x32_bf16 v[56:59], v[174:177], v[182:185], v[56:59]
	v_mfma_f32_16x16x32_bf16 v[52:55], v[166:169], v[190:193], v[52:55]
	v_mfma_f32_16x16x32_bf16 v[48:51], v[174:177], v[190:193], v[48:51]
	v_mfma_f32_16x16x32_bf16 v[44:47], v[166:169], v[198:201], v[44:47]
	v_mfma_f32_16x16x32_bf16 v[40:43], v[174:177], v[198:201], v[40:43]
	v_mfma_f32_16x16x32_bf16 v[36:39], v[166:169], v[206:209], v[36:39]
	v_mfma_f32_16x16x32_bf16 v[32:35], v[174:177], v[206:209], v[32:35]
	v_mfma_f32_16x16x32_bf16 v[60:63], v[170:173], v[186:189], v[60:63]
	v_mfma_f32_16x16x32_bf16 v[56:59], v[178:181], v[186:189], v[56:59]
	v_mfma_f32_16x16x32_bf16 v[52:55], v[170:173], v[194:197], v[52:55]
	v_mfma_f32_16x16x32_bf16 v[48:51], v[178:181], v[194:197], v[48:51]
	v_mfma_f32_16x16x32_bf16 v[44:47], v[170:173], v[202:205], v[44:47]
	v_mfma_f32_16x16x32_bf16 v[40:43], v[178:181], v[202:205], v[40:43]
	v_mfma_f32_16x16x32_bf16 v[36:39], v[170:173], v[210:213], v[36:39]
	v_mfma_f32_16x16x32_bf16 v[32:35], v[178:181], v[210:213], v[32:35]
	s_barrier
	s_add_i32 s24, s34, s94
	s_mov_b32 m0, s24
	ds_read_b128 v[182:185], v161 offset:16384
	global_load_lds_dwordx4 v132, s[52:53]
	s_add_i32 m0, s24, 0x2000
	s_add_u32 s24, s52, 0x40000
	s_addc_u32 s25, s53, 0
	s_add_i32 s50, s35, s94
	global_load_lds_dwordx4 v128, s[52:53]
	s_mov_b32 m0, s50
	ds_read_b128 v[186:189], v161 offset:17408
	global_load_lds_dwordx4 v132, s[24:25]
	s_add_i32 m0, s50, 0x2000
	ds_read_b128 v[190:193], v161 offset:18432
	global_load_lds_dwordx4 v128, s[24:25]
	s_mov_b32 m0, s0
	ds_read_b128 v[194:197], v161 offset:19456
	global_load_lds_dwordx4 v134, s[54:55]
	s_mov_b32 m0, s1
	ds_read_b128 v[198:201], v161 offset:20480
	global_load_lds_dwordx4 v130, s[54:55]
	ds_read_b128 v[202:205], v161 offset:21504
	ds_read_b128 v[206:209], v161 offset:22528
	ds_read_b128 v[210:213], v161 offset:23552
	s_waitcnt vmcnt(8)
	s_waitcnt lgkmcnt(0)
	s_barrier
	v_mfma_f32_16x16x32_bf16 v[92:95], v[144:147], v[182:185], v[92:95]
	v_mfma_f32_16x16x32_bf16 v[88:91], v[152:155], v[182:185], v[88:91]
	v_mfma_f32_16x16x32_bf16 v[84:87], v[144:147], v[190:193], v[84:87]
	v_mfma_f32_16x16x32_bf16 v[80:83], v[152:155], v[190:193], v[80:83]
	v_mfma_f32_16x16x32_bf16 v[76:79], v[144:147], v[198:201], v[76:79]
	v_mfma_f32_16x16x32_bf16 v[72:75], v[152:155], v[198:201], v[72:75]
	v_mfma_f32_16x16x32_bf16 v[68:71], v[144:147], v[206:209], v[68:71]
	v_mfma_f32_16x16x32_bf16 v[64:67], v[152:155], v[206:209], v[64:67]
	v_mfma_f32_16x16x32_bf16 v[92:95], v[148:151], v[186:189], v[92:95]
	v_mfma_f32_16x16x32_bf16 v[88:91], v[162:165], v[186:189], v[88:91]
	v_mfma_f32_16x16x32_bf16 v[84:87], v[148:151], v[194:197], v[84:87]
	v_mfma_f32_16x16x32_bf16 v[80:83], v[162:165], v[194:197], v[80:83]
	v_mfma_f32_16x16x32_bf16 v[76:79], v[148:151], v[202:205], v[76:79]
	v_mfma_f32_16x16x32_bf16 v[72:75], v[162:165], v[202:205], v[72:75]
	v_mfma_f32_16x16x32_bf16 v[68:71], v[148:151], v[210:213], v[68:71]
	v_mfma_f32_16x16x32_bf16 v[64:67], v[162:165], v[210:213], v[64:67]
	v_mfma_f32_16x16x32_bf16 v[28:31], v[166:169], v[182:185], v[28:31]
	v_mfma_f32_16x16x32_bf16 v[24:27], v[174:177], v[182:185], v[24:27]
	v_mfma_f32_16x16x32_bf16 v[20:23], v[166:169], v[190:193], v[20:23]
	v_mfma_f32_16x16x32_bf16 v[16:19], v[174:177], v[190:193], v[16:19]
	v_mfma_f32_16x16x32_bf16 v[12:15], v[166:169], v[198:201], v[12:15]
	v_mfma_f32_16x16x32_bf16 v[8:11], v[174:177], v[198:201], v[8:11]
	v_mfma_f32_16x16x32_bf16 v[4:7], v[166:169], v[206:209], v[4:7]
	v_mfma_f32_16x16x32_bf16 v[0:3], v[174:177], v[206:209], v[0:3]
	v_mfma_f32_16x16x32_bf16 v[28:31], v[170:173], v[186:189], v[28:31]
	v_mfma_f32_16x16x32_bf16 v[24:27], v[178:181], v[186:189], v[24:27]
	v_mfma_f32_16x16x32_bf16 v[20:23], v[170:173], v[194:197], v[20:23]
	v_mfma_f32_16x16x32_bf16 v[16:19], v[178:181], v[194:197], v[16:19]
	v_mfma_f32_16x16x32_bf16 v[12:15], v[170:173], v[202:205], v[12:15]
	v_mfma_f32_16x16x32_bf16 v[8:11], v[178:181], v[202:205], v[8:11]
	v_mfma_f32_16x16x32_bf16 v[4:7], v[170:173], v[210:213], v[4:7]
	v_mfma_f32_16x16x32_bf16 v[0:3], v[178:181], v[210:213], v[0:3]
	s_barrier
; #define PG8_STAGE(bufoff, gbase, voff) do { _Pragma("unroll") for (int _i = 0; _i < 2; ++_i) \
;         __builtin_amdgcn_global_load_lds((const unsigned*)((const char*)(gbase) + (voff)[_i]), (LAS unsigned*)(lds + (bufoff) + ldsw + _i * 8192), 16, 0, 0); } while (0)
; #define PG8_LDA(dst, b, h) do { _Pragma("unroll") for (int m = 0; m < 4; ++m) _Pragma("unroll") for (int k = 0; k < 2; ++k) dst[m][k] = *(const LAS bf16x8*)(lds + PG8_SA(b, h) + aoff + m * 2048 + k * 1024); } while (0)
; #define PG8_LDB(dst, b, h) do { _Pragma("unroll") for (int n = 0; n < 2; ++n) _Pragma("unroll") for (int k = 0; k < 2; ++k) dst[n][k] = *(const LAS bf16x8*)(lds + PG8_SB(b, h) + boff + n * 2048 + k * 1024); } while (0)
; #define PG8_MMA(ai, bj, At, Bt) do { __builtin_amdgcn_s_setprio(1); _Pragma("unroll") for (int m = 0; m < 4; ++m) _Pragma("unroll") for (int n = 0; n < 2; ++n) _Pragma("unroll") for (int k = 0; k < 2; ++k) \
;         acc[ai][bj][m][n] = __builtin_amdgcn_mfma_f32_16x16x32_bf16(Bt[n][k], At[m][k], acc[ai][bj][m][n], 0, 0, 0); __builtin_amdgcn_s_setprio(0); } while (0)
; #define PG8_WAIT_V(n) asm volatile("s_waitcnt vmcnt(" #n ")" ::: "memory")
; #define PG8_WAIT_L(n) asm volatile("s_waitcnt lgkmcnt(" #n ")" ::: "memory")
; #define PG8_BAR __builtin_amdgcn_s_barrier()
; #define PG8_SCHED __builtin_amdgcn_sched_barrier(0)
; template <class Epi>
; __device__ __forceinline__ void gemm_phase(LAS unsigned char* lds, const Gemm g, const StaticOrder& S, const Epi& E, const int wid) {
;     ...
;             PG8_LDB(B0, 1, 0); PG8_LDB(B1, 1, 1); PG8_SCHED; PG8_LDA(At, 1, 0); PG8_STAGE(PG8_SA(0, 1), a2 + hstepA, voffA);
;             PG8_WAIT_V(8); PG8_WAIT_L(0); PG8_BAR; PG8_MMA(0, 0, At, B0); PG8_MMA(0, 1, At, B1); PG8_BAR; PG8_SCHED;
;             PG8_LDA(At, 1, 1); PG8_STAGE(PG8_SB(1, 0), b3, voffB); PG8_STAGE(PG8_SB(1, 1), b3 + hstepB, voffB); PG8_STAGE(PG8_SA(1, 0), a3, voffA);
;             PG8_WAIT_V(8); PG8_WAIT_L(0); PG8_BAR; PG8_MMA(1, 0, At, B0); PG8_MMA(1, 1, At, B1); PG8_BAR; PG8_SCHED;
;         }
;         if (wr == 0) PG8_BAR;
	s_add_i32 s50, 0, 0x18000
	s_add_i32 s51, 0, 0x1c000
	v_add_u32_e32 v162, s50, v156
	v_add_u32_e32 v178, s51, v156
	ds_read_b128 v[144:147], v162
	ds_read_b128 v[148:151], v162 offset:1024
	ds_read_b128 v[152:155], v162 offset:2048
	ds_read_b128 v[162:165], v162 offset:3072
	ds_read_b128 v[166:169], v178
	ds_read_b128 v[170:173], v178 offset:1024
	ds_read_b128 v[174:177], v178 offset:2048
	ds_read_b128 v[178:181], v178 offset:3072
	s_add_u32 s24, s54, 0x40000
	s_addc_u32 s25, s55, 0
	s_mov_b32 m0, s15
	ds_read_b128 v[182:185], v161 offset:32768
	global_load_lds_dwordx4 v134, s[24:25]
	s_mov_b32 m0, s26
	ds_read_b128 v[186:189], v161 offset:33792
	global_load_lds_dwordx4 v130, s[24:25]
	ds_read_b128 v[190:193], v161 offset:34816
	ds_read_b128 v[194:197], v161 offset:35840
	ds_read_b128 v[198:201], v161 offset:36864
	ds_read_b128 v[202:205], v161 offset:37888
	ds_read_b128 v[206:209], v161 offset:38912
	ds_read_b128 v[210:213], v161 offset:39936
	s_waitcnt vmcnt(8)
	s_waitcnt lgkmcnt(0)
	s_barrier
	v_mfma_f32_16x16x32_bf16 v[124:127], v[144:147], v[182:185], v[124:127]
	v_mfma_f32_16x16x32_bf16 v[120:123], v[152:155], v[182:185], v[120:123]
	v_mfma_f32_16x16x32_bf16 v[116:119], v[144:147], v[190:193], v[116:119]
	v_mfma_f32_16x16x32_bf16 v[112:115], v[152:155], v[190:193], v[112:115]
	v_mfma_f32_16x16x32_bf16 v[108:111], v[144:147], v[198:201], v[108:111]
	v_mfma_f32_16x16x32_bf16 v[104:107], v[152:155], v[198:201], v[104:107]
	v_mfma_f32_16x16x32_bf16 v[100:103], v[144:147], v[206:209], v[100:103]
	v_mfma_f32_16x16x32_bf16 v[96:99], v[152:155], v[206:209], v[96:99]
	v_mfma_f32_16x16x32_bf16 v[124:127], v[148:151], v[186:189], v[124:127]
	v_mfma_f32_16x16x32_bf16 v[120:123], v[162:165], v[186:189], v[120:123]
	v_mfma_f32_16x16x32_bf16 v[116:119], v[148:151], v[194:197], v[116:119]
	v_mfma_f32_16x16x32_bf16 v[112:115], v[162:165], v[194:197], v[112:115]
	v_mfma_f32_16x16x32_bf16 v[108:111], v[148:151], v[202:205], v[108:111]
	v_mfma_f32_16x16x32_bf16 v[104:107], v[162:165], v[202:205], v[104:107]
	v_mfma_f32_16x16x32_bf16 v[100:103], v[148:151], v[210:213], v[100:103]
	v_mfma_f32_16x16x32_bf16 v[96:99], v[162:165], v[210:213], v[96:99]
	v_mfma_f32_16x16x32_bf16 v[60:63], v[166:169], v[182:185], v[60:63]
	v_mfma_f32_16x16x32_bf16 v[56:59], v[174:177], v[182:185], v[56:59]
	v_mfma_f32_16x16x32_bf16 v[52:55], v[166:169], v[190:193], v[52:55]
	v_mfma_f32_16x16x32_bf16 v[48:51], v[174:177], v[190:193], v[48:51]
	v_mfma_f32_16x16x32_bf16 v[44:47], v[166:169], v[198:201], v[44:47]
	v_mfma_f32_16x16x32_bf16 v[40:43], v[174:177], v[198:201], v[40:43]
	v_mfma_f32_16x16x32_bf16 v[36:39], v[166:169], v[206:209], v[36:39]
	v_mfma_f32_16x16x32_bf16 v[32:35], v[174:177], v[206:209], v[32:35]
	v_mfma_f32_16x16x32_bf16 v[60:63], v[170:173], v[186:189], v[60:63]
	v_mfma_f32_16x16x32_bf16 v[56:59], v[178:181], v[186:189], v[56:59]
	v_mfma_f32_16x16x32_bf16 v[52:55], v[170:173], v[194:197], v[52:55]
	v_mfma_f32_16x16x32_bf16 v[48:51], v[178:181], v[194:197], v[48:51]
	v_mfma_f32_16x16x32_bf16 v[44:47], v[170:173], v[202:205], v[44:47]
	v_mfma_f32_16x16x32_bf16 v[40:43], v[178:181], v[202:205], v[40:43]
	v_mfma_f32_16x16x32_bf16 v[36:39], v[170:173], v[210:213], v[36:39]
	v_mfma_f32_16x16x32_bf16 v[32:35], v[178:181], v[210:213], v[32:35]
	s_barrier
	s_add_i32 s24, s50, s94
	s_add_u32 s98, s52, 0x80
	s_addc_u32 s99, s53, 0
	s_mov_b32 m0, s24
	ds_read_b128 v[182:185], v161 offset:49152
	global_load_lds_dwordx4 v132, s[98:99]
	s_add_i32 m0, s24, 0x2000
	s_add_u32 s24, s52, 0x40080
	s_addc_u32 s25, s53, 0
	s_add_i32 s50, s51, s94
	global_load_lds_dwordx4 v128, s[98:99]
	s_mov_b32 m0, s50
	ds_read_b128 v[186:189], v161 offset:50176
	global_load_lds_dwordx4 v132, s[24:25]
	s_add_i32 m0, s50, 0x2000
	ds_read_b128 v[190:193], v161 offset:51200
	global_load_lds_dwordx4 v128, s[24:25]
	s_add_u32 s100, s54, 0x80
	s_addc_u32 s101, s55, 0
	s_mov_b32 m0, s28
	ds_read_b128 v[194:197], v161 offset:52224
	global_load_lds_dwordx4 v134, s[100:101]
	s_mov_b32 m0, s29
	ds_read_b128 v[198:201], v161 offset:53248
	global_load_lds_dwordx4 v130, s[100:101]
	ds_read_b128 v[202:205], v161 offset:54272
	ds_read_b128 v[206:209], v161 offset:55296
	ds_read_b128 v[210:213], v161 offset:56320
	s_waitcnt vmcnt(8)
	s_waitcnt lgkmcnt(0)
	s_barrier
	v_mfma_f32_16x16x32_bf16 v[92:95], v[144:147], v[182:185], v[92:95]
	v_mfma_f32_16x16x32_bf16 v[88:91], v[152:155], v[182:185], v[88:91]
	v_mfma_f32_16x16x32_bf16 v[84:87], v[144:147], v[190:193], v[84:87]
	v_mfma_f32_16x16x32_bf16 v[80:83], v[152:155], v[190:193], v[80:83]
	v_mfma_f32_16x16x32_bf16 v[76:79], v[144:147], v[198:201], v[76:79]
	v_mfma_f32_16x16x32_bf16 v[72:75], v[152:155], v[198:201], v[72:75]
	v_mfma_f32_16x16x32_bf16 v[68:71], v[144:147], v[206:209], v[68:71]
	v_mfma_f32_16x16x32_bf16 v[64:67], v[152:155], v[206:209], v[64:67]
	v_mfma_f32_16x16x32_bf16 v[92:95], v[148:151], v[186:189], v[92:95]
	v_mfma_f32_16x16x32_bf16 v[88:91], v[162:165], v[186:189], v[88:91]
	v_mfma_f32_16x16x32_bf16 v[84:87], v[148:151], v[194:197], v[84:87]
	v_mfma_f32_16x16x32_bf16 v[80:83], v[162:165], v[194:197], v[80:83]
	v_mfma_f32_16x16x32_bf16 v[76:79], v[148:151], v[202:205], v[76:79]
	v_mfma_f32_16x16x32_bf16 v[72:75], v[162:165], v[202:205], v[72:75]
	v_mfma_f32_16x16x32_bf16 v[68:71], v[148:151], v[210:213], v[68:71]
	v_mfma_f32_16x16x32_bf16 v[64:67], v[162:165], v[210:213], v[64:67]
	v_mfma_f32_16x16x32_bf16 v[28:31], v[166:169], v[182:185], v[28:31]
	v_mfma_f32_16x16x32_bf16 v[24:27], v[174:177], v[182:185], v[24:27]
	v_mfma_f32_16x16x32_bf16 v[20:23], v[166:169], v[190:193], v[20:23]
	v_mfma_f32_16x16x32_bf16 v[16:19], v[174:177], v[190:193], v[16:19]
	v_mfma_f32_16x16x32_bf16 v[12:15], v[166:169], v[198:201], v[12:15]
	v_mfma_f32_16x16x32_bf16 v[8:11], v[174:177], v[198:201], v[8:11]
	v_mfma_f32_16x16x32_bf16 v[4:7], v[166:169], v[206:209], v[4:7]
	v_mfma_f32_16x16x32_bf16 v[0:3], v[174:177], v[206:209], v[0:3]
	v_mfma_f32_16x16x32_bf16 v[28:31], v[170:173], v[186:189], v[28:31]
	v_mfma_f32_16x16x32_bf16 v[24:27], v[178:181], v[186:189], v[24:27]
	v_mfma_f32_16x16x32_bf16 v[20:23], v[170:173], v[194:197], v[20:23]
	v_mfma_f32_16x16x32_bf16 v[16:19], v[178:181], v[194:197], v[16:19]
	v_mfma_f32_16x16x32_bf16 v[12:15], v[170:173], v[202:205], v[12:15]
	v_mfma_f32_16x16x32_bf16 v[8:11], v[178:181], v[202:205], v[8:11]
	v_mfma_f32_16x16x32_bf16 v[4:7], v[170:173], v[210:213], v[4:7]
	v_mfma_f32_16x16x32_bf16 v[0:3], v[178:181], v[210:213], v[0:3]
	s_barrier
	s_add_i32 s58, s58, 2
	s_add_u32 s45, s45, 0x100
	s_addc_u32 s57, s57, 0
	s_cmp_gt_u32 s58, 13
	s_mov_b64 s[50:51], s[6:7]
	s_cbranch_scc0 .LBB0_1692
	s_and_b64 vcc, exec, s[22:23]
	s_cbranch_vccz .LBB0_1695
	s_barrier

; #define PG8_STAGE(bufoff, gbase, voff) do { _Pragma("unroll") for (int _i = 0; _i < 2; ++_i) \
;         __builtin_amdgcn_global_load_lds((const unsigned*)((const char*)(gbase) + (voff)[_i]), (LAS unsigned*)(lds + (bufoff) + ldsw + _i * 8192), 16, 0, 0); } while (0)
; #define PG8_LDA(dst, b, h) do { _Pragma("unroll") for (int m = 0; m < 4; ++m) _Pragma("unroll") for (int k = 0; k < 2; ++k) dst[m][k] = *(const LAS bf16x8*)(lds + PG8_SA(b, h) + aoff + m * 2048 + k * 1024); } while (0)
; #define PG8_LDB(dst, b, h) do { _Pragma("unroll") for (int n = 0; n < 2; ++n) _Pragma("unroll") for (int k = 0; k < 2; ++k) dst[n][k] = *(const LAS bf16x8*)(lds + PG8_SB(b, h) + boff + n * 2048 + k * 1024); } while (0)
; #define PG8_MMA(ai, bj, At, Bt) do { __builtin_amdgcn_s_setprio(1); _Pragma("unroll") for (int m = 0; m < 4; ++m) _Pragma("unroll") for (int n = 0; n < 2; ++n) _Pragma("unroll") for (int k = 0; k < 2; ++k) \
;         acc[ai][bj][m][n] = __builtin_amdgcn_mfma_f32_16x16x32_bf16(Bt[n][k], At[m][k], acc[ai][bj][m][n], 0, 0, 0); __builtin_amdgcn_s_setprio(0); } while (0)
; #define PG8_WAIT_V(n) asm volatile("s_waitcnt vmcnt(" #n ")" ::: "memory")
; #define PG8_WAIT_L(n) asm volatile("s_waitcnt lgkmcnt(" #n ")" ::: "memory")
; #define PG8_BAR __builtin_amdgcn_s_barrier()
; #define PG8_SCHED __builtin_amdgcn_sched_barrier(0)
; template <class Epi>
; __device__ __forceinline__ void gemm_phase(LAS unsigned char* lds, const Gemm g, const StaticOrder& S, const Epi& E, const int wid) {
;     ...
;             const bool last = (t == nt - 2);
;             const char* a1 = cA + (size_t)(t + 1) * kstep;
;             const char* a2 = last ? nA : cA + (size_t)(t + 2) * kstep; const char* b2 = last ? nB : cB + (size_t)(t + 2) * kstep;
;             const char* a3 = a2 + kstep; const char* b3 = b2 + kstep;
;             PG8_LDB(B0, 0, 0); PG8_LDB(B1, 0, 1); PG8_SCHED; PG8_LDA(At, 0, 0); PG8_STAGE(PG8_SA(1, 1), a1 + hstepA, voffA);
;             PG8_WAIT_V(8); PG8_WAIT_L(0); PG8_BAR; PG8_MMA(0, 0, At, B0); PG8_MMA(0, 1, At, B1); PG8_BAR; PG8_SCHED;
;             PG8_LDA(At, 0, 1); PG8_STAGE(PG8_SB(0, 0), b2, voffB); PG8_STAGE(PG8_SB(0, 1), b2 + hstepB, voffB); PG8_STAGE(PG8_SA(0, 0), a2, voffA);
;             PG8_WAIT_V(8); PG8_WAIT_L(0); PG8_BAR; PG8_MMA(1, 0, At, B0); PG8_MMA(1, 1, At, B1); PG8_BAR; PG8_SCHED;
.LBB0_1727:
	ds_read_b128 v[144:147], v157
	ds_read_b128 v[148:151], v157 offset:1024
	ds_read_b128 v[160:163], v157 offset:2048
	ds_read_b128 v[164:167], v157 offset:3072
	ds_read_b128 v[168:171], v158
	ds_read_b128 v[172:175], v158 offset:1024
	ds_read_b128 v[176:179], v158 offset:2048
	ds_read_b128 v[180:183], v158 offset:3072
	s_add_u32 s6, s46, 0x100
	s_addc_u32 s7, s47, 0
	s_cmp_eq_u32 s54, 28
	s_cselect_b32 s51, s43, s7
	s_cselect_b32 s50, s42, s6
	s_cselect_b32 s49, s21, s53
	s_cselect_b32 s48, s41, s52
	s_add_i32 m0, s1, 0xc000
	ds_read_b128 v[184:187], v159
	global_load_lds_dwordx4 v136, s[46:47]
	s_add_i32 m0, s1, 0xe000
	ds_read_b128 v[188:191], v159 offset:1024
	global_load_lds_dwordx4 v138, s[46:47]
	ds_read_b128 v[192:195], v159 offset:2048
	ds_read_b128 v[196:199], v159 offset:3072
	ds_read_b128 v[200:203], v159 offset:4096
	ds_read_b128 v[204:207], v159 offset:5120
	ds_read_b128 v[208:211], v159 offset:6144
	ds_read_b128 v[212:215], v159 offset:7168
	s_waitcnt vmcnt(8)
	s_waitcnt lgkmcnt(0)
	s_barrier
	v_mfma_f32_16x16x32_bf16 v[124:127], v[144:147], v[184:187], v[124:127]
	v_mfma_f32_16x16x32_bf16 v[120:123], v[160:163], v[184:187], v[120:123]
	v_mfma_f32_16x16x32_bf16 v[116:119], v[144:147], v[192:195], v[116:119]
	v_mfma_f32_16x16x32_bf16 v[112:115], v[160:163], v[192:195], v[112:115]
	v_mfma_f32_16x16x32_bf16 v[108:111], v[144:147], v[200:203], v[108:111]
	v_mfma_f32_16x16x32_bf16 v[104:107], v[160:163], v[200:203], v[104:107]
	v_mfma_f32_16x16x32_bf16 v[100:103], v[144:147], v[208:211], v[100:103]
	v_mfma_f32_16x16x32_bf16 v[96:99], v[160:163], v[208:211], v[96:99]
	v_mfma_f32_16x16x32_bf16 v[124:127], v[148:151], v[188:191], v[124:127]
	v_mfma_f32_16x16x32_bf16 v[120:123], v[164:167], v[188:191], v[120:123]
	v_mfma_f32_16x16x32_bf16 v[116:119], v[148:151], v[196:199], v[116:119]
	v_mfma_f32_16x16x32_bf16 v[112:115], v[164:167], v[196:199], v[112:115]
	v_mfma_f32_16x16x32_bf16 v[108:111], v[148:151], v[204:207], v[108:111]
	v_mfma_f32_16x16x32_bf16 v[104:107], v[164:167], v[204:207], v[104:107]
	v_mfma_f32_16x16x32_bf16 v[100:103], v[148:151], v[212:215], v[100:103]
	v_mfma_f32_16x16x32_bf16 v[96:99], v[164:167], v[212:215], v[96:99]
	v_mfma_f32_16x16x32_bf16 v[76:79], v[168:171], v[184:187], v[76:79]
	v_mfma_f32_16x16x32_bf16 v[64:67], v[176:179], v[184:187], v[64:67]
	v_mfma_f32_16x16x32_bf16 v[56:59], v[168:171], v[192:195], v[56:59]
	v_mfma_f32_16x16x32_bf16 v[48:51], v[176:179], v[192:195], v[48:51]
	v_mfma_f32_16x16x32_bf16 v[44:47], v[168:171], v[200:203], v[44:47]
	v_mfma_f32_16x16x32_bf16 v[40:43], v[176:179], v[200:203], v[40:43]
	v_mfma_f32_16x16x32_bf16 v[36:39], v[168:171], v[208:211], v[36:39]
	v_mfma_f32_16x16x32_bf16 v[32:35], v[176:179], v[208:211], v[32:35]
	v_mfma_f32_16x16x32_bf16 v[76:79], v[172:175], v[188:191], v[76:79]
	v_mfma_f32_16x16x32_bf16 v[64:67], v[180:183], v[188:191], v[64:67]
	v_mfma_f32_16x16x32_bf16 v[56:59], v[172:175], v[196:199], v[56:59]
	v_mfma_f32_16x16x32_bf16 v[48:51], v[180:183], v[196:199], v[48:51]
	v_mfma_f32_16x16x32_bf16 v[44:47], v[172:175], v[204:207], v[44:47]
	v_mfma_f32_16x16x32_bf16 v[40:43], v[180:183], v[204:207], v[40:43]
	v_mfma_f32_16x16x32_bf16 v[36:39], v[172:175], v[212:215], v[36:39]
	v_mfma_f32_16x16x32_bf16 v[32:35], v[180:183], v[212:215], v[32:35]
	s_barrier
	s_add_i32 s24, s35, s94
	s_mov_b32 m0, s24
	ds_read_b128 v[184:187], v159 offset:16384
	global_load_lds_dwordx4 v132, s[48:49]
	s_add_i32 m0, s24, 0x2000
	s_add_u32 s24, s48, 0x80000
	s_addc_u32 s25, s49, 0
	s_add_i32 s46, s36, s94
	global_load_lds_dwordx4 v128, s[48:49]
	s_mov_b32 m0, s46
	ds_read_b128 v[188:191], v159 offset:17408
	global_load_lds_dwordx4 v132, s[24:25]
	s_add_i32 m0, s46, 0x2000
	ds_read_b128 v[192:195], v159 offset:18432
	global_load_lds_dwordx4 v128, s[24:25]
	s_mov_b32 m0, s1
	ds_read_b128 v[196:199], v159 offset:19456
	global_load_lds_dwordx4 v134, s[50:51]
	s_mov_b32 m0, s15
	ds_read_b128 v[200:203], v159 offset:20480
	global_load_lds_dwordx4 v130, s[50:51]
	ds_read_b128 v[204:207], v159 offset:21504
	ds_read_b128 v[208:211], v159 offset:22528
	ds_read_b128 v[212:215], v159 offset:23552
	s_waitcnt vmcnt(8)
	s_waitcnt lgkmcnt(0)
	s_barrier
	v_mfma_f32_16x16x32_bf16 v[92:95], v[144:147], v[184:187], v[92:95]
	v_mfma_f32_16x16x32_bf16 v[88:91], v[160:163], v[184:187], v[88:91]
	v_mfma_f32_16x16x32_bf16 v[84:87], v[144:147], v[192:195], v[84:87]
	v_mfma_f32_16x16x32_bf16 v[80:83], v[160:163], v[192:195], v[80:83]
	v_mfma_f32_16x16x32_bf16 v[72:75], v[144:147], v[200:203], v[72:75]
	v_mfma_f32_16x16x32_bf16 v[68:71], v[160:163], v[200:203], v[68:71]
	v_mfma_f32_16x16x32_bf16 v[60:63], v[144:147], v[208:211], v[60:63]
	v_mfma_f32_16x16x32_bf16 v[52:55], v[160:163], v[208:211], v[52:55]
	v_mfma_f32_16x16x32_bf16 v[92:95], v[148:151], v[188:191], v[92:95]
	v_mfma_f32_16x16x32_bf16 v[88:91], v[164:167], v[188:191], v[88:91]
	v_mfma_f32_16x16x32_bf16 v[84:87], v[148:151], v[196:199], v[84:87]
	v_mfma_f32_16x16x32_bf16 v[80:83], v[164:167], v[196:199], v[80:83]
	v_mfma_f32_16x16x32_bf16 v[72:75], v[148:151], v[204:207], v[72:75]
	v_mfma_f32_16x16x32_bf16 v[68:71], v[164:167], v[204:207], v[68:71]
	v_mfma_f32_16x16x32_bf16 v[60:63], v[148:151], v[212:215], v[60:63]
	v_mfma_f32_16x16x32_bf16 v[52:55], v[164:167], v[212:215], v[52:55]
	v_mfma_f32_16x16x32_bf16 v[28:31], v[168:171], v[184:187], v[28:31]
	v_mfma_f32_16x16x32_bf16 v[24:27], v[176:179], v[184:187], v[24:27]
	v_mfma_f32_16x16x32_bf16 v[20:23], v[168:171], v[192:195], v[20:23]
	v_mfma_f32_16x16x32_bf16 v[16:19], v[176:179], v[192:195], v[16:19]
	v_mfma_f32_16x16x32_bf16 v[12:15], v[168:171], v[200:203], v[12:15]
	v_mfma_f32_16x16x32_bf16 v[8:11], v[176:179], v[200:203], v[8:11]
	v_mfma_f32_16x16x32_bf16 v[4:7], v[168:171], v[208:211], v[4:7]
	v_mfma_f32_16x16x32_bf16 v[0:3], v[176:179], v[208:211], v[0:3]
	v_mfma_f32_16x16x32_bf16 v[28:31], v[172:175], v[188:191], v[28:31]
	v_mfma_f32_16x16x32_bf16 v[24:27], v[180:183], v[188:191], v[24:27]
	v_mfma_f32_16x16x32_bf16 v[20:23], v[172:175], v[196:199], v[20:23]
	v_mfma_f32_16x16x32_bf16 v[16:19], v[180:183], v[196:199], v[16:19]
	v_mfma_f32_16x16x32_bf16 v[12:15], v[172:175], v[204:207], v[12:15]
	v_mfma_f32_16x16x32_bf16 v[8:11], v[180:183], v[204:207], v[8:11]
	v_mfma_f32_16x16x32_bf16 v[4:7], v[172:175], v[212:215], v[4:7]
	v_mfma_f32_16x16x32_bf16 v[0:3], v[180:183], v[212:215], v[0:3]
	s_barrier
; #define PG8_STAGE(bufoff, gbase, voff) do { _Pragma("unroll") for (int _i = 0; _i < 2; ++_i) \
;         __builtin_amdgcn_global_load_lds((const unsigned*)((const char*)(gbase) + (voff)[_i]), (LAS unsigned*)(lds + (bufoff) + ldsw + _i * 8192), 16, 0, 0); } while (0)
; #define PG8_LDA(dst, b, h) do { _Pragma("unroll") for (int m = 0; m < 4; ++m) _Pragma("unroll") for (int k = 0; k < 2; ++k) dst[m][k] = *(const LAS bf16x8*)(lds + PG8_SA(b, h) + aoff + m * 2048 + k * 1024); } while (0)
; #define PG8_LDB(dst, b, h) do { _Pragma("unroll") for (int n = 0; n < 2; ++n) _Pragma("unroll") for (int k = 0; k < 2; ++k) dst[n][k] = *(const LAS bf16x8*)(lds + PG8_SB(b, h) + boff + n * 2048 + k * 1024); } while (0)
; #define PG8_MMA(ai, bj, At, Bt) do { __builtin_amdgcn_s_setprio(1); _Pragma("unroll") for (int m = 0; m < 4; ++m) _Pragma("unroll") for (int n = 0; n < 2; ++n) _Pragma("unroll") for (int k = 0; k < 2; ++k) \
;         acc[ai][bj][m][n] = __builtin_amdgcn_mfma_f32_16x16x32_bf16(Bt[n][k], At[m][k], acc[ai][bj][m][n], 0, 0, 0); __builtin_amdgcn_s_setprio(0); } while (0)
; #define PG8_WAIT_V(n) asm volatile("s_waitcnt vmcnt(" #n ")" ::: "memory")
; #define PG8_WAIT_L(n) asm volatile("s_waitcnt lgkmcnt(" #n ")" ::: "memory")
; #define PG8_BAR __builtin_amdgcn_s_barrier()
; #define PG8_SCHED __builtin_amdgcn_sched_barrier(0)
; template <class Epi>
; __device__ __forceinline__ void gemm_phase(LAS unsigned char* lds, const Gemm g, const StaticOrder& S, const Epi& E, const int wid) {
;     ...
;             PG8_LDB(B0, 1, 0); PG8_LDB(B1, 1, 1); PG8_SCHED; PG8_LDA(At, 1, 0); PG8_STAGE(PG8_SA(0, 1), a2 + hstepA, voffA);
;             PG8_WAIT_V(8); PG8_WAIT_L(0); PG8_BAR; PG8_MMA(0, 0, At, B0); PG8_MMA(0, 1, At, B1); PG8_BAR; PG8_SCHED;
;             PG8_LDA(At, 1, 1); PG8_STAGE(PG8_SB(1, 0), b3, voffB); PG8_STAGE(PG8_SB(1, 1), b3 + hstepB, voffB); PG8_STAGE(PG8_SA(1, 0), a3, voffA);
;             PG8_WAIT_V(8); PG8_WAIT_L(0); PG8_BAR; PG8_MMA(1, 0, At, B0); PG8_MMA(1, 1, At, B1); PG8_BAR; PG8_SCHED;
;         }
;         if (wr == 0) PG8_BAR;
	s_add_i32 s46, 0, 0x18000
	s_add_i32 s47, 0, 0x1c000
	v_add_u32_e32 v164, s46, v154
	v_add_u32_e32 v180, s47, v154
	ds_read_b128 v[144:147], v164
	ds_read_b128 v[148:151], v164 offset:1024
	ds_read_b128 v[160:163], v164 offset:2048
	ds_read_b128 v[164:167], v164 offset:3072
	ds_read_b128 v[168:171], v180
	ds_read_b128 v[172:175], v180 offset:1024
	ds_read_b128 v[176:179], v180 offset:2048
	ds_read_b128 v[180:183], v180 offset:3072
	s_add_u32 s24, s50, 0x80000
	s_addc_u32 s25, s51, 0
	s_mov_b32 m0, s26
	ds_read_b128 v[184:187], v159 offset:32768
	global_load_lds_dwordx4 v134, s[24:25]
	s_mov_b32 m0, s27
	ds_read_b128 v[188:191], v159 offset:33792
	global_load_lds_dwordx4 v130, s[24:25]
	ds_read_b128 v[192:195], v159 offset:34816
	ds_read_b128 v[196:199], v159 offset:35840
	ds_read_b128 v[200:203], v159 offset:36864
	ds_read_b128 v[204:207], v159 offset:37888
	ds_read_b128 v[208:211], v159 offset:38912
	ds_read_b128 v[212:215], v159 offset:39936
	s_waitcnt vmcnt(8)
	s_waitcnt lgkmcnt(0)
	s_barrier
	v_mfma_f32_16x16x32_bf16 v[124:127], v[144:147], v[184:187], v[124:127]
	v_mfma_f32_16x16x32_bf16 v[120:123], v[160:163], v[184:187], v[120:123]
	v_mfma_f32_16x16x32_bf16 v[116:119], v[144:147], v[192:195], v[116:119]
	v_mfma_f32_16x16x32_bf16 v[112:115], v[160:163], v[192:195], v[112:115]
	v_mfma_f32_16x16x32_bf16 v[108:111], v[144:147], v[200:203], v[108:111]
	v_mfma_f32_16x16x32_bf16 v[104:107], v[160:163], v[200:203], v[104:107]
	v_mfma_f32_16x16x32_bf16 v[100:103], v[144:147], v[208:211], v[100:103]
	v_mfma_f32_16x16x32_bf16 v[96:99], v[160:163], v[208:211], v[96:99]
	v_mfma_f32_16x16x32_bf16 v[124:127], v[148:151], v[188:191], v[124:127]
	v_mfma_f32_16x16x32_bf16 v[120:123], v[164:167], v[188:191], v[120:123]
	v_mfma_f32_16x16x32_bf16 v[116:119], v[148:151], v[196:199], v[116:119]
	v_mfma_f32_16x16x32_bf16 v[112:115], v[164:167], v[196:199], v[112:115]
	v_mfma_f32_16x16x32_bf16 v[108:111], v[148:151], v[204:207], v[108:111]
	v_mfma_f32_16x16x32_bf16 v[104:107], v[164:167], v[204:207], v[104:107]
	v_mfma_f32_16x16x32_bf16 v[100:103], v[148:151], v[212:215], v[100:103]
	v_mfma_f32_16x16x32_bf16 v[96:99], v[164:167], v[212:215], v[96:99]
	v_mfma_f32_16x16x32_bf16 v[76:79], v[168:171], v[184:187], v[76:79]
	v_mfma_f32_16x16x32_bf16 v[64:67], v[176:179], v[184:187], v[64:67]
	v_mfma_f32_16x16x32_bf16 v[56:59], v[168:171], v[192:195], v[56:59]
	v_mfma_f32_16x16x32_bf16 v[48:51], v[176:179], v[192:195], v[48:51]
	v_mfma_f32_16x16x32_bf16 v[44:47], v[168:171], v[200:203], v[44:47]
	v_mfma_f32_16x16x32_bf16 v[40:43], v[176:179], v[200:203], v[40:43]
	v_mfma_f32_16x16x32_bf16 v[36:39], v[168:171], v[208:211], v[36:39]
	v_mfma_f32_16x16x32_bf16 v[32:35], v[176:179], v[208:211], v[32:35]
	v_mfma_f32_16x16x32_bf16 v[76:79], v[172:175], v[188:191], v[76:79]
	v_mfma_f32_16x16x32_bf16 v[64:67], v[180:183], v[188:191], v[64:67]
	v_mfma_f32_16x16x32_bf16 v[56:59], v[172:175], v[196:199], v[56:59]
	v_mfma_f32_16x16x32_bf16 v[48:51], v[180:183], v[196:199], v[48:51]
	v_mfma_f32_16x16x32_bf16 v[44:47], v[172:175], v[204:207], v[44:47]
	v_mfma_f32_16x16x32_bf16 v[40:43], v[180:183], v[204:207], v[40:43]
	v_mfma_f32_16x16x32_bf16 v[36:39], v[172:175], v[212:215], v[36:39]
	v_mfma_f32_16x16x32_bf16 v[32:35], v[180:183], v[212:215], v[32:35]
	s_barrier
	s_add_i32 s24, s46, s94
	s_add_u32 s98, s48, 0x80
	s_addc_u32 s99, s49, 0
	s_mov_b32 m0, s24
	ds_read_b128 v[184:187], v159 offset:49152
	global_load_lds_dwordx4 v132, s[98:99]
	s_add_i32 m0, s24, 0x2000
	s_add_u32 s24, s48, 0x80080
	s_addc_u32 s25, s49, 0
	s_add_i32 s46, s47, s94
	global_load_lds_dwordx4 v128, s[98:99]
	s_mov_b32 m0, s46
	ds_read_b128 v[188:191], v159 offset:50176
	global_load_lds_dwordx4 v132, s[24:25]
	s_add_i32 m0, s46, 0x2000
	ds_read_b128 v[192:195], v159 offset:51200
	global_load_lds_dwordx4 v128, s[24:25]
	s_add_u32 s100, s50, 0x80
	s_addc_u32 s101, s51, 0
	s_mov_b32 m0, s29
	ds_read_b128 v[196:199], v159 offset:52224
	global_load_lds_dwordx4 v134, s[100:101]
	s_mov_b32 m0, s34
	ds_read_b128 v[200:203], v159 offset:53248
	global_load_lds_dwordx4 v130, s[100:101]
	ds_read_b128 v[204:207], v159 offset:54272
	ds_read_b128 v[208:211], v159 offset:55296
	ds_read_b128 v[212:215], v159 offset:56320
	s_waitcnt vmcnt(8)
	s_waitcnt lgkmcnt(0)
	s_barrier
	v_mfma_f32_16x16x32_bf16 v[92:95], v[144:147], v[184:187], v[92:95]
	v_mfma_f32_16x16x32_bf16 v[88:91], v[160:163], v[184:187], v[88:91]
	v_mfma_f32_16x16x32_bf16 v[84:87], v[144:147], v[192:195], v[84:87]
	v_mfma_f32_16x16x32_bf16 v[80:83], v[160:163], v[192:195], v[80:83]
	v_mfma_f32_16x16x32_bf16 v[72:75], v[144:147], v[200:203], v[72:75]
	v_mfma_f32_16x16x32_bf16 v[68:71], v[160:163], v[200:203], v[68:71]
	v_mfma_f32_16x16x32_bf16 v[60:63], v[144:147], v[208:211], v[60:63]
	v_mfma_f32_16x16x32_bf16 v[52:55], v[160:163], v[208:211], v[52:55]
	v_mfma_f32_16x16x32_bf16 v[92:95], v[148:151], v[188:191], v[92:95]
	v_mfma_f32_16x16x32_bf16 v[88:91], v[164:167], v[188:191], v[88:91]
	v_mfma_f32_16x16x32_bf16 v[84:87], v[148:151], v[196:199], v[84:87]
	v_mfma_f32_16x16x32_bf16 v[80:83], v[164:167], v[196:199], v[80:83]
	v_mfma_f32_16x16x32_bf16 v[72:75], v[148:151], v[204:207], v[72:75]
	v_mfma_f32_16x16x32_bf16 v[68:71], v[164:167], v[204:207], v[68:71]
	v_mfma_f32_16x16x32_bf16 v[60:63], v[148:151], v[212:215], v[60:63]
	v_mfma_f32_16x16x32_bf16 v[52:55], v[164:167], v[212:215], v[52:55]
	v_mfma_f32_16x16x32_bf16 v[28:31], v[168:171], v[184:187], v[28:31]
	v_mfma_f32_16x16x32_bf16 v[24:27], v[176:179], v[184:187], v[24:27]
	v_mfma_f32_16x16x32_bf16 v[20:23], v[168:171], v[192:195], v[20:23]
	v_mfma_f32_16x16x32_bf16 v[16:19], v[176:179], v[192:195], v[16:19]
	v_mfma_f32_16x16x32_bf16 v[12:15], v[168:171], v[200:203], v[12:15]
	v_mfma_f32_16x16x32_bf16 v[8:11], v[176:179], v[200:203], v[8:11]
	v_mfma_f32_16x16x32_bf16 v[4:7], v[168:171], v[208:211], v[4:7]
	v_mfma_f32_16x16x32_bf16 v[0:3], v[176:179], v[208:211], v[0:3]
	v_mfma_f32_16x16x32_bf16 v[28:31], v[172:175], v[188:191], v[28:31]
	v_mfma_f32_16x16x32_bf16 v[24:27], v[180:183], v[188:191], v[24:27]
	v_mfma_f32_16x16x32_bf16 v[20:23], v[172:175], v[196:199], v[20:23]
	v_mfma_f32_16x16x32_bf16 v[16:19], v[180:183], v[196:199], v[16:19]
	v_mfma_f32_16x16x32_bf16 v[12:15], v[172:175], v[204:207], v[12:15]
	v_mfma_f32_16x16x32_bf16 v[8:11], v[180:183], v[204:207], v[8:11]
	v_mfma_f32_16x16x32_bf16 v[4:7], v[172:175], v[212:215], v[4:7]
	v_mfma_f32_16x16x32_bf16 v[0:3], v[180:183], v[212:215], v[0:3]
	s_barrier
	s_add_i32 s54, s54, 2
	s_add_u32 s52, s52, 0x100
	s_addc_u32 s53, s53, 0
	s_cmp_gt_u32 s54, 29
	s_mov_b64 s[46:47], s[6:7]
	s_cbranch_scc0 .LBB0_1727
	s_and_b64 vcc, exec, s[22:23]
	s_cbranch_vccz .LBB0_1730
	s_barrier

; #define PG8_STAGE(bufoff, gbase, voff) do { _Pragma("unroll") for (int _i = 0; _i < 2; ++_i) \
;         __builtin_amdgcn_global_load_lds((const unsigned*)((const char*)(gbase) + (voff)[_i]), (LAS unsigned*)(lds + (bufoff) + ldsw + _i * 8192), 16, 0, 0); } while (0)
; #define PG8_LDA(dst, b, h) do { _Pragma("unroll") for (int m = 0; m < 4; ++m) _Pragma("unroll") for (int k = 0; k < 2; ++k) dst[m][k] = *(const LAS bf16x8*)(lds + PG8_SA(b, h) + aoff + m * 2048 + k * 1024); } while (0)
; #define PG8_LDB(dst, b, h) do { _Pragma("unroll") for (int n = 0; n < 2; ++n) _Pragma("unroll") for (int k = 0; k < 2; ++k) dst[n][k] = *(const LAS bf16x8*)(lds + PG8_SB(b, h) + boff + n * 2048 + k * 1024); } while (0)
; #define PG8_MMA(ai, bj, At, Bt) do { __builtin_amdgcn_s_setprio(1); _Pragma("unroll") for (int m = 0; m < 4; ++m) _Pragma("unroll") for (int n = 0; n < 2; ++n) _Pragma("unroll") for (int k = 0; k < 2; ++k) \
;         acc[ai][bj][m][n] = __builtin_amdgcn_mfma_f32_16x16x32_bf16(Bt[n][k], At[m][k], acc[ai][bj][m][n], 0, 0, 0); __builtin_amdgcn_s_setprio(0); } while (0)
; #define PG8_WAIT_V(n) asm volatile("s_waitcnt vmcnt(" #n ")" ::: "memory")
; #define PG8_WAIT_L(n) asm volatile("s_waitcnt lgkmcnt(" #n ")" ::: "memory")
; #define PG8_BAR __builtin_amdgcn_s_barrier()
; #define PG8_SCHED __builtin_amdgcn_sched_barrier(0)
; template <class Epi>
; __device__ __forceinline__ void gemm_phase(LAS unsigned char* lds, const Gemm g, const StaticOrder& S, const Epi& E, const int wid) {
;     ...
;         for (int t = 0; t < nt; t += 2) {
;             const bool last = (t == nt - 2);
;             const char* a1 = cA + (size_t)(t + 1) * kstep;
;             const char* a2 = last ? nA : cA + (size_t)(t + 2) * kstep; const char* b2 = last ? nB : cB + (size_t)(t + 2) * kstep;
;             const char* a3 = a2 + kstep; const char* b3 = b2 + kstep;
;             PG8_LDB(B0, 0, 0); PG8_LDB(B1, 0, 1); PG8_SCHED; PG8_LDA(At, 0, 0); PG8_STAGE(PG8_SA(1, 1), a1 + hstepA, voffA);
;             PG8_WAIT_V(8); PG8_WAIT_L(0); PG8_BAR; PG8_MMA(0, 0, At, B0); PG8_MMA(0, 1, At, B1); PG8_BAR; PG8_SCHED;
;             PG8_LDA(At, 0, 1); PG8_STAGE(PG8_SB(0, 0), b2, voffB); PG8_STAGE(PG8_SB(0, 1), b2 + hstepB, voffB); PG8_STAGE(PG8_SA(0, 0), a2, voffA);
;             PG8_WAIT_V(8); PG8_WAIT_L(0); PG8_BAR; PG8_MMA(1, 0, At, B0); PG8_MMA(1, 1, At, B1); PG8_BAR; PG8_SCHED;
.LBB0_1773:
	ds_read_b128 v[150:153], v147
	ds_read_b128 v[154:157], v147 offset:1024
	ds_read_b128 v[158:161], v147 offset:2048
	ds_read_b128 v[162:165], v147 offset:3072
	ds_read_b128 v[166:169], v148
	ds_read_b128 v[170:173], v148 offset:1024
	ds_read_b128 v[174:177], v148 offset:2048
	ds_read_b128 v[178:181], v148 offset:3072
	s_add_u32 s6, s42, 0x100
	s_addc_u32 s7, s43, 0
	s_cmp_eq_u32 s54, 28
	s_cselect_b32 s47, s21, s7
	s_cselect_b32 s46, s20, s6
	s_cselect_b32 s45, s19, s53
	s_cselect_b32 s44, s51, s52
	s_add_i32 m0, s15, 0xc000
	ds_read_b128 v[182:185], v149
	global_load_lds_dwordx4 v136, s[42:43]
	s_add_i32 m0, s15, 0xe000
	ds_read_b128 v[186:189], v149 offset:1024
	global_load_lds_dwordx4 v138, s[42:43]
	ds_read_b128 v[190:193], v149 offset:2048
	ds_read_b128 v[194:197], v149 offset:3072
	ds_read_b128 v[198:201], v149 offset:4096
	ds_read_b128 v[202:205], v149 offset:5120
	ds_read_b128 v[206:209], v149 offset:6144
	ds_read_b128 v[210:213], v149 offset:7168
	s_waitcnt vmcnt(8)
	s_waitcnt lgkmcnt(0)
	s_barrier
	v_mfma_f32_16x16x32_bf16 v[124:127], v[150:153], v[182:185], v[124:127]
	v_mfma_f32_16x16x32_bf16 v[120:123], v[158:161], v[182:185], v[120:123]
	v_mfma_f32_16x16x32_bf16 v[108:111], v[150:153], v[190:193], v[108:111]
	v_mfma_f32_16x16x32_bf16 v[104:107], v[158:161], v[190:193], v[104:107]
	v_mfma_f32_16x16x32_bf16 v[92:95], v[150:153], v[198:201], v[92:95]
	v_mfma_f32_16x16x32_bf16 v[88:91], v[158:161], v[198:201], v[88:91]
	v_mfma_f32_16x16x32_bf16 v[76:79], v[150:153], v[206:209], v[76:79]
	v_mfma_f32_16x16x32_bf16 v[72:75], v[158:161], v[206:209], v[72:75]
	v_mfma_f32_16x16x32_bf16 v[124:127], v[154:157], v[186:189], v[124:127]
	v_mfma_f32_16x16x32_bf16 v[120:123], v[162:165], v[186:189], v[120:123]
	v_mfma_f32_16x16x32_bf16 v[108:111], v[154:157], v[194:197], v[108:111]
	v_mfma_f32_16x16x32_bf16 v[104:107], v[162:165], v[194:197], v[104:107]
	v_mfma_f32_16x16x32_bf16 v[92:95], v[154:157], v[202:205], v[92:95]
	v_mfma_f32_16x16x32_bf16 v[88:91], v[162:165], v[202:205], v[88:91]
	v_mfma_f32_16x16x32_bf16 v[76:79], v[154:157], v[210:213], v[76:79]
	v_mfma_f32_16x16x32_bf16 v[72:75], v[162:165], v[210:213], v[72:75]
	v_mfma_f32_16x16x32_bf16 v[116:119], v[166:169], v[182:185], v[116:119]
	v_mfma_f32_16x16x32_bf16 v[112:115], v[174:177], v[182:185], v[112:115]
	v_mfma_f32_16x16x32_bf16 v[100:103], v[166:169], v[190:193], v[100:103]
	v_mfma_f32_16x16x32_bf16 v[96:99], v[174:177], v[190:193], v[96:99]
	v_mfma_f32_16x16x32_bf16 v[84:87], v[166:169], v[198:201], v[84:87]
	v_mfma_f32_16x16x32_bf16 v[80:83], v[174:177], v[198:201], v[80:83]
	v_mfma_f32_16x16x32_bf16 v[68:71], v[166:169], v[206:209], v[68:71]
	v_mfma_f32_16x16x32_bf16 v[64:67], v[174:177], v[206:209], v[64:67]
	v_mfma_f32_16x16x32_bf16 v[116:119], v[170:173], v[186:189], v[116:119]
	v_mfma_f32_16x16x32_bf16 v[112:115], v[178:181], v[186:189], v[112:115]
	v_mfma_f32_16x16x32_bf16 v[100:103], v[170:173], v[194:197], v[100:103]
	v_mfma_f32_16x16x32_bf16 v[96:99], v[178:181], v[194:197], v[96:99]
	v_mfma_f32_16x16x32_bf16 v[84:87], v[170:173], v[202:205], v[84:87]
	v_mfma_f32_16x16x32_bf16 v[80:83], v[178:181], v[202:205], v[80:83]
	v_mfma_f32_16x16x32_bf16 v[68:71], v[170:173], v[210:213], v[68:71]
	v_mfma_f32_16x16x32_bf16 v[64:67], v[178:181], v[210:213], v[64:67]
	s_barrier
	s_add_i32 s24, s36, s94
	s_mov_b32 m0, s24
	ds_read_b128 v[182:185], v149 offset:16384
	global_load_lds_dwordx4 v132, s[44:45]
	s_add_i32 m0, s24, 0x2000
	s_add_u32 s24, s44, 0x80000
	s_addc_u32 s25, s45, 0
	s_add_i32 s42, s37, s94
	global_load_lds_dwordx4 v128, s[44:45]
	s_mov_b32 m0, s42
	ds_read_b128 v[186:189], v149 offset:17408
	global_load_lds_dwordx4 v132, s[24:25]
	s_add_i32 m0, s42, 0x2000
	ds_read_b128 v[190:193], v149 offset:18432
	global_load_lds_dwordx4 v128, s[24:25]
	s_mov_b32 m0, s15
	ds_read_b128 v[194:197], v149 offset:19456
	global_load_lds_dwordx4 v134, s[46:47]
	s_mov_b32 m0, s26
	ds_read_b128 v[198:201], v149 offset:20480
	global_load_lds_dwordx4 v130, s[46:47]
	ds_read_b128 v[202:205], v149 offset:21504
	ds_read_b128 v[206:209], v149 offset:22528
	ds_read_b128 v[210:213], v149 offset:23552
	s_waitcnt vmcnt(8)
	s_waitcnt lgkmcnt(0)
	s_barrier
	v_mfma_f32_16x16x32_bf16 v[60:63], v[150:153], v[182:185], v[60:63]
	v_mfma_f32_16x16x32_bf16 v[56:59], v[158:161], v[182:185], v[56:59]
	v_mfma_f32_16x16x32_bf16 v[44:47], v[150:153], v[190:193], v[44:47]
	v_mfma_f32_16x16x32_bf16 v[40:43], v[158:161], v[190:193], v[40:43]
	v_mfma_f32_16x16x32_bf16 v[28:31], v[150:153], v[198:201], v[28:31]
	v_mfma_f32_16x16x32_bf16 v[24:27], v[158:161], v[198:201], v[24:27]
	v_mfma_f32_16x16x32_bf16 v[12:15], v[150:153], v[206:209], v[12:15]
	v_mfma_f32_16x16x32_bf16 v[8:11], v[158:161], v[206:209], v[8:11]
	v_mfma_f32_16x16x32_bf16 v[60:63], v[154:157], v[186:189], v[60:63]
	v_mfma_f32_16x16x32_bf16 v[56:59], v[162:165], v[186:189], v[56:59]
	v_mfma_f32_16x16x32_bf16 v[44:47], v[154:157], v[194:197], v[44:47]
	v_mfma_f32_16x16x32_bf16 v[40:43], v[162:165], v[194:197], v[40:43]
	v_mfma_f32_16x16x32_bf16 v[28:31], v[154:157], v[202:205], v[28:31]
	v_mfma_f32_16x16x32_bf16 v[24:27], v[162:165], v[202:205], v[24:27]
	v_mfma_f32_16x16x32_bf16 v[12:15], v[154:157], v[210:213], v[12:15]
	v_mfma_f32_16x16x32_bf16 v[8:11], v[162:165], v[210:213], v[8:11]
	v_mfma_f32_16x16x32_bf16 v[52:55], v[166:169], v[182:185], v[52:55]
	v_mfma_f32_16x16x32_bf16 v[48:51], v[174:177], v[182:185], v[48:51]
	v_mfma_f32_16x16x32_bf16 v[36:39], v[166:169], v[190:193], v[36:39]
	v_mfma_f32_16x16x32_bf16 v[32:35], v[174:177], v[190:193], v[32:35]
	v_mfma_f32_16x16x32_bf16 v[20:23], v[166:169], v[198:201], v[20:23]
	v_mfma_f32_16x16x32_bf16 v[16:19], v[174:177], v[198:201], v[16:19]
	v_mfma_f32_16x16x32_bf16 v[4:7], v[166:169], v[206:209], v[4:7]
	v_mfma_f32_16x16x32_bf16 v[0:3], v[174:177], v[206:209], v[0:3]
	v_mfma_f32_16x16x32_bf16 v[52:55], v[170:173], v[186:189], v[52:55]
	v_mfma_f32_16x16x32_bf16 v[48:51], v[178:181], v[186:189], v[48:51]
	v_mfma_f32_16x16x32_bf16 v[36:39], v[170:173], v[194:197], v[36:39]
	v_mfma_f32_16x16x32_bf16 v[32:35], v[178:181], v[194:197], v[32:35]
	v_mfma_f32_16x16x32_bf16 v[20:23], v[170:173], v[202:205], v[20:23]
	v_mfma_f32_16x16x32_bf16 v[16:19], v[178:181], v[202:205], v[16:19]
	v_mfma_f32_16x16x32_bf16 v[4:7], v[170:173], v[210:213], v[4:7]
	v_mfma_f32_16x16x32_bf16 v[0:3], v[178:181], v[210:213], v[0:3]
	s_barrier
; #define PG8_STAGE(bufoff, gbase, voff) do { _Pragma("unroll") for (int _i = 0; _i < 2; ++_i) \
;         __builtin_amdgcn_global_load_lds((const unsigned*)((const char*)(gbase) + (voff)[_i]), (LAS unsigned*)(lds + (bufoff) + ldsw + _i * 8192), 16, 0, 0); } while (0)
; #define PG8_LDA(dst, b, h) do { _Pragma("unroll") for (int m = 0; m < 4; ++m) _Pragma("unroll") for (int k = 0; k < 2; ++k) dst[m][k] = *(const LAS bf16x8*)(lds + PG8_SA(b, h) + aoff + m * 2048 + k * 1024); } while (0)
; #define PG8_LDB(dst, b, h) do { _Pragma("unroll") for (int n = 0; n < 2; ++n) _Pragma("unroll") for (int k = 0; k < 2; ++k) dst[n][k] = *(const LAS bf16x8*)(lds + PG8_SB(b, h) + boff + n * 2048 + k * 1024); } while (0)
; #define PG8_MMA(ai, bj, At, Bt) do { __builtin_amdgcn_s_setprio(1); _Pragma("unroll") for (int m = 0; m < 4; ++m) _Pragma("unroll") for (int n = 0; n < 2; ++n) _Pragma("unroll") for (int k = 0; k < 2; ++k) \
;         acc[ai][bj][m][n] = __builtin_amdgcn_mfma_f32_16x16x32_bf16(Bt[n][k], At[m][k], acc[ai][bj][m][n], 0, 0, 0); __builtin_amdgcn_s_setprio(0); } while (0)
; #define PG8_WAIT_V(n) asm volatile("s_waitcnt vmcnt(" #n ")" ::: "memory")
; #define PG8_WAIT_L(n) asm volatile("s_waitcnt lgkmcnt(" #n ")" ::: "memory")
; #define PG8_BAR __builtin_amdgcn_s_barrier()
; #define PG8_SCHED __builtin_amdgcn_sched_barrier(0)
; template <class Epi>
; __device__ __forceinline__ void gemm_phase(LAS unsigned char* lds, const Gemm g, const StaticOrder& S, const Epi& E, const int wid) {
;     ...
;             PG8_LDB(B0, 1, 0); PG8_LDB(B1, 1, 1); PG8_SCHED; PG8_LDA(At, 1, 0); PG8_STAGE(PG8_SA(0, 1), a2 + hstepA, voffA);
;             PG8_WAIT_V(8); PG8_WAIT_L(0); PG8_BAR; PG8_MMA(0, 0, At, B0); PG8_MMA(0, 1, At, B1); PG8_BAR; PG8_SCHED;
;             PG8_LDA(At, 1, 1); PG8_STAGE(PG8_SB(1, 0), b3, voffB); PG8_STAGE(PG8_SB(1, 1), b3 + hstepB, voffB); PG8_STAGE(PG8_SA(1, 0), a3, voffA);
;             PG8_WAIT_V(8); PG8_WAIT_L(0); PG8_BAR; PG8_MMA(1, 0, At, B0); PG8_MMA(1, 1, At, B1); PG8_BAR; PG8_SCHED;
;         }
;         if (wr == 0) PG8_BAR;
	s_add_i32 s42, 0, 0x18000
	s_add_i32 s43, 0, 0x1c000
	v_add_u32_e32 v162, s42, v144
	v_add_u32_e32 v178, s43, v144
	ds_read_b128 v[150:153], v162
	ds_read_b128 v[154:157], v162 offset:1024
	ds_read_b128 v[158:161], v162 offset:2048
	ds_read_b128 v[162:165], v162 offset:3072
	ds_read_b128 v[166:169], v178
	ds_read_b128 v[170:173], v178 offset:1024
	ds_read_b128 v[174:177], v178 offset:2048
	ds_read_b128 v[178:181], v178 offset:3072
	s_add_u32 s24, s46, 0x80000
	s_addc_u32 s25, s47, 0
	s_mov_b32 m0, s27
	ds_read_b128 v[182:185], v149 offset:32768
	global_load_lds_dwordx4 v134, s[24:25]
	s_mov_b32 m0, s28
	ds_read_b128 v[186:189], v149 offset:33792
	global_load_lds_dwordx4 v130, s[24:25]
	ds_read_b128 v[190:193], v149 offset:34816
	ds_read_b128 v[194:197], v149 offset:35840
	ds_read_b128 v[198:201], v149 offset:36864
	ds_read_b128 v[202:205], v149 offset:37888
	ds_read_b128 v[206:209], v149 offset:38912
	ds_read_b128 v[210:213], v149 offset:39936
	s_waitcnt vmcnt(8)
	s_waitcnt lgkmcnt(0)
	s_barrier
	v_mfma_f32_16x16x32_bf16 v[124:127], v[150:153], v[182:185], v[124:127]
	v_mfma_f32_16x16x32_bf16 v[120:123], v[158:161], v[182:185], v[120:123]
	v_mfma_f32_16x16x32_bf16 v[108:111], v[150:153], v[190:193], v[108:111]
	v_mfma_f32_16x16x32_bf16 v[104:107], v[158:161], v[190:193], v[104:107]
	v_mfma_f32_16x16x32_bf16 v[92:95], v[150:153], v[198:201], v[92:95]
	v_mfma_f32_16x16x32_bf16 v[88:91], v[158:161], v[198:201], v[88:91]
	v_mfma_f32_16x16x32_bf16 v[76:79], v[150:153], v[206:209], v[76:79]
	v_mfma_f32_16x16x32_bf16 v[72:75], v[158:161], v[206:209], v[72:75]
	v_mfma_f32_16x16x32_bf16 v[124:127], v[154:157], v[186:189], v[124:127]
	v_mfma_f32_16x16x32_bf16 v[120:123], v[162:165], v[186:189], v[120:123]
	v_mfma_f32_16x16x32_bf16 v[108:111], v[154:157], v[194:197], v[108:111]
	v_mfma_f32_16x16x32_bf16 v[104:107], v[162:165], v[194:197], v[104:107]
	v_mfma_f32_16x16x32_bf16 v[92:95], v[154:157], v[202:205], v[92:95]
	v_mfma_f32_16x16x32_bf16 v[88:91], v[162:165], v[202:205], v[88:91]
	v_mfma_f32_16x16x32_bf16 v[76:79], v[154:157], v[210:213], v[76:79]
	v_mfma_f32_16x16x32_bf16 v[72:75], v[162:165], v[210:213], v[72:75]
	v_mfma_f32_16x16x32_bf16 v[116:119], v[166:169], v[182:185], v[116:119]
	v_mfma_f32_16x16x32_bf16 v[112:115], v[174:177], v[182:185], v[112:115]
	v_mfma_f32_16x16x32_bf16 v[100:103], v[166:169], v[190:193], v[100:103]
	v_mfma_f32_16x16x32_bf16 v[96:99], v[174:177], v[190:193], v[96:99]
	v_mfma_f32_16x16x32_bf16 v[84:87], v[166:169], v[198:201], v[84:87]
	v_mfma_f32_16x16x32_bf16 v[80:83], v[174:177], v[198:201], v[80:83]
	v_mfma_f32_16x16x32_bf16 v[68:71], v[166:169], v[206:209], v[68:71]
	v_mfma_f32_16x16x32_bf16 v[64:67], v[174:177], v[206:209], v[64:67]
	v_mfma_f32_16x16x32_bf16 v[116:119], v[170:173], v[186:189], v[116:119]
	v_mfma_f32_16x16x32_bf16 v[112:115], v[178:181], v[186:189], v[112:115]
	v_mfma_f32_16x16x32_bf16 v[100:103], v[170:173], v[194:197], v[100:103]
	v_mfma_f32_16x16x32_bf16 v[96:99], v[178:181], v[194:197], v[96:99]
	v_mfma_f32_16x16x32_bf16 v[84:87], v[170:173], v[202:205], v[84:87]
	v_mfma_f32_16x16x32_bf16 v[80:83], v[178:181], v[202:205], v[80:83]
	v_mfma_f32_16x16x32_bf16 v[68:71], v[170:173], v[210:213], v[68:71]
	v_mfma_f32_16x16x32_bf16 v[64:67], v[178:181], v[210:213], v[64:67]
	s_barrier
	s_add_i32 s24, s42, s94
	s_add_u32 s98, s44, 0x80
	s_addc_u32 s99, s45, 0
	s_mov_b32 m0, s24
	ds_read_b128 v[182:185], v149 offset:49152
	global_load_lds_dwordx4 v132, s[98:99]
	s_add_i32 m0, s24, 0x2000
	s_add_u32 s24, s44, 0x80080
	s_addc_u32 s25, s45, 0
	s_add_i32 s42, s43, s94
	global_load_lds_dwordx4 v128, s[98:99]
	s_mov_b32 m0, s42
	ds_read_b128 v[186:189], v149 offset:50176
	global_load_lds_dwordx4 v132, s[24:25]
	s_add_i32 m0, s42, 0x2000
	ds_read_b128 v[190:193], v149 offset:51200
	global_load_lds_dwordx4 v128, s[24:25]
	s_add_u32 s100, s46, 0x80
	s_addc_u32 s101, s47, 0
	s_mov_b32 m0, s34
	ds_read_b128 v[194:197], v149 offset:52224
	global_load_lds_dwordx4 v134, s[100:101]
	s_mov_b32 m0, s35
	ds_read_b128 v[198:201], v149 offset:53248
	global_load_lds_dwordx4 v130, s[100:101]
	ds_read_b128 v[202:205], v149 offset:54272
	ds_read_b128 v[206:209], v149 offset:55296
	ds_read_b128 v[210:213], v149 offset:56320
	s_waitcnt vmcnt(8)
	s_waitcnt lgkmcnt(0)
	s_barrier
	v_mfma_f32_16x16x32_bf16 v[60:63], v[150:153], v[182:185], v[60:63]
	v_mfma_f32_16x16x32_bf16 v[56:59], v[158:161], v[182:185], v[56:59]
	v_mfma_f32_16x16x32_bf16 v[44:47], v[150:153], v[190:193], v[44:47]
	v_mfma_f32_16x16x32_bf16 v[40:43], v[158:161], v[190:193], v[40:43]
	v_mfma_f32_16x16x32_bf16 v[28:31], v[150:153], v[198:201], v[28:31]
	v_mfma_f32_16x16x32_bf16 v[24:27], v[158:161], v[198:201], v[24:27]
	v_mfma_f32_16x16x32_bf16 v[12:15], v[150:153], v[206:209], v[12:15]
	v_mfma_f32_16x16x32_bf16 v[8:11], v[158:161], v[206:209], v[8:11]
	v_mfma_f32_16x16x32_bf16 v[60:63], v[154:157], v[186:189], v[60:63]
	v_mfma_f32_16x16x32_bf16 v[56:59], v[162:165], v[186:189], v[56:59]
	v_mfma_f32_16x16x32_bf16 v[44:47], v[154:157], v[194:197], v[44:47]
	v_mfma_f32_16x16x32_bf16 v[40:43], v[162:165], v[194:197], v[40:43]
	v_mfma_f32_16x16x32_bf16 v[28:31], v[154:157], v[202:205], v[28:31]
	v_mfma_f32_16x16x32_bf16 v[24:27], v[162:165], v[202:205], v[24:27]
	v_mfma_f32_16x16x32_bf16 v[12:15], v[154:157], v[210:213], v[12:15]
	v_mfma_f32_16x16x32_bf16 v[8:11], v[162:165], v[210:213], v[8:11]
	v_mfma_f32_16x16x32_bf16 v[52:55], v[166:169], v[182:185], v[52:55]
	v_mfma_f32_16x16x32_bf16 v[48:51], v[174:177], v[182:185], v[48:51]
	v_mfma_f32_16x16x32_bf16 v[36:39], v[166:169], v[190:193], v[36:39]
	v_mfma_f32_16x16x32_bf16 v[32:35], v[174:177], v[190:193], v[32:35]
	v_mfma_f32_16x16x32_bf16 v[20:23], v[166:169], v[198:201], v[20:23]
	v_mfma_f32_16x16x32_bf16 v[16:19], v[174:177], v[198:201], v[16:19]
	v_mfma_f32_16x16x32_bf16 v[4:7], v[166:169], v[206:209], v[4:7]
	v_mfma_f32_16x16x32_bf16 v[0:3], v[174:177], v[206:209], v[0:3]
	v_mfma_f32_16x16x32_bf16 v[52:55], v[170:173], v[186:189], v[52:55]
	v_mfma_f32_16x16x32_bf16 v[48:51], v[178:181], v[186:189], v[48:51]
	v_mfma_f32_16x16x32_bf16 v[36:39], v[170:173], v[194:197], v[36:39]
	v_mfma_f32_16x16x32_bf16 v[32:35], v[178:181], v[194:197], v[32:35]
	v_mfma_f32_16x16x32_bf16 v[20:23], v[170:173], v[202:205], v[20:23]
	v_mfma_f32_16x16x32_bf16 v[16:19], v[178:181], v[202:205], v[16:19]
	v_mfma_f32_16x16x32_bf16 v[4:7], v[170:173], v[210:213], v[4:7]
	v_mfma_f32_16x16x32_bf16 v[0:3], v[178:181], v[210:213], v[0:3]
	s_barrier
	s_add_i32 s54, s54, 2
	s_add_u32 s52, s52, 0x100
	s_addc_u32 s53, s53, 0
	s_cmp_gt_u32 s54, 29
	s_mov_b64 s[42:43], s[6:7]
	s_cbranch_scc0 .LBB0_1773
	s_and_b64 vcc, exec, s[22:23]
	s_cbranch_vccz .LBB0_1776
	s_barrier

; #define PG8_STAGE(bufoff, gbase, voff) do { _Pragma("unroll") for (int _i = 0; _i < 2; ++_i) \
;         __builtin_amdgcn_global_load_lds((const unsigned*)((const char*)(gbase) + (voff)[_i]), (LAS unsigned*)(lds + (bufoff) + ldsw + _i * 8192), 16, 0, 0); } while (0)
; #define PG8_LDA(dst, b, h) do { _Pragma("unroll") for (int m = 0; m < 4; ++m) _Pragma("unroll") for (int k = 0; k < 2; ++k) dst[m][k] = *(const LAS bf16x8*)(lds + PG8_SA(b, h) + aoff + m * 2048 + k * 1024); } while (0)
; #define PG8_LDB(dst, b, h) do { _Pragma("unroll") for (int n = 0; n < 2; ++n) _Pragma("unroll") for (int k = 0; k < 2; ++k) dst[n][k] = *(const LAS bf16x8*)(lds + PG8_SB(b, h) + boff + n * 2048 + k * 1024); } while (0)
; #define PG8_MMA(ai, bj, At, Bt) do { __builtin_amdgcn_s_setprio(1); _Pragma("unroll") for (int m = 0; m < 4; ++m) _Pragma("unroll") for (int n = 0; n < 2; ++n) _Pragma("unroll") for (int k = 0; k < 2; ++k) \
;         acc[ai][bj][m][n] = __builtin_amdgcn_mfma_f32_16x16x32_bf16(Bt[n][k], At[m][k], acc[ai][bj][m][n], 0, 0, 0); __builtin_amdgcn_s_setprio(0); } while (0)
; #define PG8_WAIT_V(n) asm volatile("s_waitcnt vmcnt(" #n ")" ::: "memory")
; #define PG8_WAIT_L(n) asm volatile("s_waitcnt lgkmcnt(" #n ")" ::: "memory")
; #define PG8_BAR __builtin_amdgcn_s_barrier()
; #define PG8_SCHED __builtin_amdgcn_sched_barrier(0)
; template <class Epi>
; __device__ __forceinline__ void gemm_phase(LAS unsigned char* lds, const Gemm g, const StaticOrder& S, const Epi& E, const int wid) {
;     ...
;         for (int t = 0; t < nt; t += 2) {
;             const bool last = (t == nt - 2);
;             const char* a1 = cA + (size_t)(t + 1) * kstep;
;             const char* a2 = last ? nA : cA + (size_t)(t + 2) * kstep; const char* b2 = last ? nB : cB + (size_t)(t + 2) * kstep;
;             const char* a3 = a2 + kstep; const char* b3 = b2 + kstep;
;             PG8_LDB(B0, 0, 0); PG8_LDB(B1, 0, 1); PG8_SCHED; PG8_LDA(At, 0, 0); PG8_STAGE(PG8_SA(1, 1), a1 + hstepA, voffA);
;             PG8_WAIT_V(8); PG8_WAIT_L(0); PG8_BAR; PG8_MMA(0, 0, At, B0); PG8_MMA(0, 1, At, B1); PG8_BAR; PG8_SCHED;
;             PG8_LDA(At, 0, 1); PG8_STAGE(PG8_SB(0, 0), b2, voffB); PG8_STAGE(PG8_SB(0, 1), b2 + hstepB, voffB); PG8_STAGE(PG8_SA(0, 0), a2, voffA);
;             PG8_WAIT_V(8); PG8_WAIT_L(0); PG8_BAR; PG8_MMA(1, 0, At, B0); PG8_MMA(1, 1, At, B1); PG8_BAR; PG8_SCHED;
.LBB0_1810:
	ds_read_b128 v[144:147], v153
	ds_read_b128 v[156:159], v153 offset:1024
	ds_read_b128 v[160:163], v153 offset:2048
	ds_read_b128 v[164:167], v153 offset:3072
	ds_read_b128 v[168:171], v154
	ds_read_b128 v[172:175], v154 offset:1024
	ds_read_b128 v[176:179], v154 offset:2048
	ds_read_b128 v[180:183], v154 offset:3072
	s_add_u32 s26, s20, 0x100
	s_addc_u32 s27, s21, 0
	s_cmpk_eq_i32 s45, 0x54
	s_cselect_b32 s31, s7, s27
	s_cselect_b32 s30, s6, s26
	s_cselect_b32 s29, s19, s44
	s_cselect_b32 s28, s18, s43
	s_add_i32 m0, s1, 0xc000
	ds_read_b128 v[184:187], v155
	global_load_lds_dwordx4 v136, s[20:21]
	s_add_i32 m0, s1, 0xe000
	ds_read_b128 v[188:191], v155 offset:1024
	global_load_lds_dwordx4 v138, s[20:21]
	ds_read_b128 v[192:195], v155 offset:2048
	ds_read_b128 v[196:199], v155 offset:3072
	ds_read_b128 v[200:203], v155 offset:4096
	ds_read_b128 v[204:207], v155 offset:5120
	ds_read_b128 v[208:211], v155 offset:6144
	ds_read_b128 v[212:215], v155 offset:7168
	s_waitcnt vmcnt(8)
	s_waitcnt lgkmcnt(0)
	s_barrier
	v_mfma_f32_16x16x32_bf16 v[124:127], v[144:147], v[184:187], v[124:127]
	v_mfma_f32_16x16x32_bf16 v[120:123], v[160:163], v[184:187], v[120:123]
	v_mfma_f32_16x16x32_bf16 v[116:119], v[144:147], v[192:195], v[116:119]
	v_mfma_f32_16x16x32_bf16 v[112:115], v[160:163], v[192:195], v[112:115]
	v_mfma_f32_16x16x32_bf16 v[108:111], v[144:147], v[200:203], v[108:111]
	v_mfma_f32_16x16x32_bf16 v[104:107], v[160:163], v[200:203], v[104:107]
	v_mfma_f32_16x16x32_bf16 v[100:103], v[144:147], v[208:211], v[100:103]
	v_mfma_f32_16x16x32_bf16 v[96:99], v[160:163], v[208:211], v[96:99]
	v_mfma_f32_16x16x32_bf16 v[124:127], v[156:159], v[188:191], v[124:127]
	v_mfma_f32_16x16x32_bf16 v[120:123], v[164:167], v[188:191], v[120:123]
	v_mfma_f32_16x16x32_bf16 v[116:119], v[156:159], v[196:199], v[116:119]
	v_mfma_f32_16x16x32_bf16 v[112:115], v[164:167], v[196:199], v[112:115]
	v_mfma_f32_16x16x32_bf16 v[108:111], v[156:159], v[204:207], v[108:111]
	v_mfma_f32_16x16x32_bf16 v[104:107], v[164:167], v[204:207], v[104:107]
	v_mfma_f32_16x16x32_bf16 v[100:103], v[156:159], v[212:215], v[100:103]
	v_mfma_f32_16x16x32_bf16 v[96:99], v[164:167], v[212:215], v[96:99]
	v_mfma_f32_16x16x32_bf16 v[68:71], v[168:171], v[184:187], v[68:71]
	v_mfma_f32_16x16x32_bf16 v[64:67], v[176:179], v[184:187], v[64:67]
	v_mfma_f32_16x16x32_bf16 v[52:55], v[168:171], v[192:195], v[52:55]
	v_mfma_f32_16x16x32_bf16 v[48:51], v[176:179], v[192:195], v[48:51]
	v_mfma_f32_16x16x32_bf16 v[44:47], v[168:171], v[200:203], v[44:47]
	v_mfma_f32_16x16x32_bf16 v[40:43], v[176:179], v[200:203], v[40:43]
	v_mfma_f32_16x16x32_bf16 v[36:39], v[168:171], v[208:211], v[36:39]
	v_mfma_f32_16x16x32_bf16 v[32:35], v[176:179], v[208:211], v[32:35]
	v_mfma_f32_16x16x32_bf16 v[68:71], v[172:175], v[188:191], v[68:71]
	v_mfma_f32_16x16x32_bf16 v[64:67], v[180:183], v[188:191], v[64:67]
	v_mfma_f32_16x16x32_bf16 v[52:55], v[172:175], v[196:199], v[52:55]
	v_mfma_f32_16x16x32_bf16 v[48:51], v[180:183], v[196:199], v[48:51]
	v_mfma_f32_16x16x32_bf16 v[44:47], v[172:175], v[204:207], v[44:47]
	v_mfma_f32_16x16x32_bf16 v[40:43], v[180:183], v[204:207], v[40:43]
	v_mfma_f32_16x16x32_bf16 v[36:39], v[172:175], v[212:215], v[36:39]
	v_mfma_f32_16x16x32_bf16 v[32:35], v[180:183], v[212:215], v[32:35]
	s_barrier
	s_add_i32 s20, s0, s94
	s_mov_b32 m0, s20
	ds_read_b128 v[184:187], v155 offset:16384
	global_load_lds_dwordx4 v132, s[28:29]
	s_add_i32 m0, s20, 0x2000
	s_add_u32 s20, s28, 0x160000
	s_addc_u32 s21, s29, 0
	s_add_i32 s24, s38, s94
	global_load_lds_dwordx4 v128, s[28:29]
	s_mov_b32 m0, s24
	ds_read_b128 v[188:191], v155 offset:17408
	global_load_lds_dwordx4 v132, s[20:21]
	s_add_i32 m0, s24, 0x2000
	ds_read_b128 v[192:195], v155 offset:18432
	global_load_lds_dwordx4 v128, s[20:21]
	s_mov_b32 m0, s1
	ds_read_b128 v[196:199], v155 offset:19456
	global_load_lds_dwordx4 v134, s[30:31]
	s_mov_b32 m0, s12
	ds_read_b128 v[200:203], v155 offset:20480
	global_load_lds_dwordx4 v130, s[30:31]
	ds_read_b128 v[204:207], v155 offset:21504
	ds_read_b128 v[208:211], v155 offset:22528
	ds_read_b128 v[212:215], v155 offset:23552
	s_waitcnt vmcnt(8)
	s_waitcnt lgkmcnt(0)
	s_barrier
	v_mfma_f32_16x16x32_bf16 v[92:95], v[144:147], v[184:187], v[92:95]
	v_mfma_f32_16x16x32_bf16 v[88:91], v[160:163], v[184:187], v[88:91]
	v_mfma_f32_16x16x32_bf16 v[84:87], v[144:147], v[192:195], v[84:87]
	v_mfma_f32_16x16x32_bf16 v[80:83], v[160:163], v[192:195], v[80:83]
	v_mfma_f32_16x16x32_bf16 v[76:79], v[144:147], v[200:203], v[76:79]
	v_mfma_f32_16x16x32_bf16 v[72:75], v[160:163], v[200:203], v[72:75]
	v_mfma_f32_16x16x32_bf16 v[60:63], v[144:147], v[208:211], v[60:63]
	v_mfma_f32_16x16x32_bf16 v[56:59], v[160:163], v[208:211], v[56:59]
	v_mfma_f32_16x16x32_bf16 v[92:95], v[156:159], v[188:191], v[92:95]
	v_mfma_f32_16x16x32_bf16 v[88:91], v[164:167], v[188:191], v[88:91]
	v_mfma_f32_16x16x32_bf16 v[84:87], v[156:159], v[196:199], v[84:87]
	v_mfma_f32_16x16x32_bf16 v[80:83], v[164:167], v[196:199], v[80:83]
	v_mfma_f32_16x16x32_bf16 v[76:79], v[156:159], v[204:207], v[76:79]
	v_mfma_f32_16x16x32_bf16 v[72:75], v[164:167], v[204:207], v[72:75]
	v_mfma_f32_16x16x32_bf16 v[60:63], v[156:159], v[212:215], v[60:63]
	v_mfma_f32_16x16x32_bf16 v[56:59], v[164:167], v[212:215], v[56:59]
	v_mfma_f32_16x16x32_bf16 v[28:31], v[168:171], v[184:187], v[28:31]
	v_mfma_f32_16x16x32_bf16 v[24:27], v[176:179], v[184:187], v[24:27]
	v_mfma_f32_16x16x32_bf16 v[20:23], v[168:171], v[192:195], v[20:23]
	v_mfma_f32_16x16x32_bf16 v[16:19], v[176:179], v[192:195], v[16:19]
	v_mfma_f32_16x16x32_bf16 v[12:15], v[168:171], v[200:203], v[12:15]
	v_mfma_f32_16x16x32_bf16 v[8:11], v[176:179], v[200:203], v[8:11]
	v_mfma_f32_16x16x32_bf16 v[4:7], v[168:171], v[208:211], v[4:7]
	v_mfma_f32_16x16x32_bf16 v[0:3], v[176:179], v[208:211], v[0:3]
	v_mfma_f32_16x16x32_bf16 v[28:31], v[172:175], v[188:191], v[28:31]
	v_mfma_f32_16x16x32_bf16 v[24:27], v[180:183], v[188:191], v[24:27]
	v_mfma_f32_16x16x32_bf16 v[20:23], v[172:175], v[196:199], v[20:23]
	v_mfma_f32_16x16x32_bf16 v[16:19], v[180:183], v[196:199], v[16:19]
	v_mfma_f32_16x16x32_bf16 v[12:15], v[172:175], v[204:207], v[12:15]
	v_mfma_f32_16x16x32_bf16 v[8:11], v[180:183], v[204:207], v[8:11]
	v_mfma_f32_16x16x32_bf16 v[4:7], v[172:175], v[212:215], v[4:7]
	v_mfma_f32_16x16x32_bf16 v[0:3], v[180:183], v[212:215], v[0:3]
	s_barrier
; #define PG8_STAGE(bufoff, gbase, voff) do { _Pragma("unroll") for (int _i = 0; _i < 2; ++_i) \
;         __builtin_amdgcn_global_load_lds((const unsigned*)((const char*)(gbase) + (voff)[_i]), (LAS unsigned*)(lds + (bufoff) + ldsw + _i * 8192), 16, 0, 0); } while (0)
; #define PG8_LDA(dst, b, h) do { _Pragma("unroll") for (int m = 0; m < 4; ++m) _Pragma("unroll") for (int k = 0; k < 2; ++k) dst[m][k] = *(const LAS bf16x8*)(lds + PG8_SA(b, h) + aoff + m * 2048 + k * 1024); } while (0)
; #define PG8_LDB(dst, b, h) do { _Pragma("unroll") for (int n = 0; n < 2; ++n) _Pragma("unroll") for (int k = 0; k < 2; ++k) dst[n][k] = *(const LAS bf16x8*)(lds + PG8_SB(b, h) + boff + n * 2048 + k * 1024); } while (0)
; #define PG8_MMA(ai, bj, At, Bt) do { __builtin_amdgcn_s_setprio(1); _Pragma("unroll") for (int m = 0; m < 4; ++m) _Pragma("unroll") for (int n = 0; n < 2; ++n) _Pragma("unroll") for (int k = 0; k < 2; ++k) \
;         acc[ai][bj][m][n] = __builtin_amdgcn_mfma_f32_16x16x32_bf16(Bt[n][k], At[m][k], acc[ai][bj][m][n], 0, 0, 0); __builtin_amdgcn_s_setprio(0); } while (0)
; #define PG8_WAIT_V(n) asm volatile("s_waitcnt vmcnt(" #n ")" ::: "memory")
; #define PG8_WAIT_L(n) asm volatile("s_waitcnt lgkmcnt(" #n ")" ::: "memory")
; #define PG8_BAR __builtin_amdgcn_s_barrier()
; #define PG8_SCHED __builtin_amdgcn_sched_barrier(0)
; template <class Epi>
; __device__ __forceinline__ void gemm_phase(LAS unsigned char* lds, const Gemm g, const StaticOrder& S, const Epi& E, const int wid) {
;     ...
;             PG8_LDB(B0, 1, 0); PG8_LDB(B1, 1, 1); PG8_SCHED; PG8_LDA(At, 1, 0); PG8_STAGE(PG8_SA(0, 1), a2 + hstepA, voffA);
;             PG8_WAIT_V(8); PG8_WAIT_L(0); PG8_BAR; PG8_MMA(0, 0, At, B0); PG8_MMA(0, 1, At, B1); PG8_BAR; PG8_SCHED;
;             PG8_LDA(At, 1, 1); PG8_STAGE(PG8_SB(1, 0), b3, voffB); PG8_STAGE(PG8_SB(1, 1), b3 + hstepB, voffB); PG8_STAGE(PG8_SA(1, 0), a3, voffA);
;             PG8_WAIT_V(8); PG8_WAIT_L(0); PG8_BAR; PG8_MMA(1, 0, At, B0); PG8_MMA(1, 1, At, B1); PG8_BAR; PG8_SCHED;
;         }
;         if (wr == 0) PG8_BAR;
	s_add_i32 s24, 0, 0x18000
	s_add_i32 s25, 0, 0x1c000
	v_add_u32_e32 v164, s24, v150
	v_add_u32_e32 v180, s25, v150
	ds_read_b128 v[144:147], v164
	ds_read_b128 v[156:159], v164 offset:1024
	ds_read_b128 v[160:163], v164 offset:2048
	ds_read_b128 v[164:167], v164 offset:3072
	ds_read_b128 v[168:171], v180
	ds_read_b128 v[172:175], v180 offset:1024
	ds_read_b128 v[176:179], v180 offset:2048
	ds_read_b128 v[180:183], v180 offset:3072
	s_add_u32 s20, s30, 0x160000
	s_addc_u32 s21, s31, 0
	s_mov_b32 m0, s15
	ds_read_b128 v[184:187], v155 offset:32768
	global_load_lds_dwordx4 v134, s[20:21]
	s_mov_b32 m0, s34
	ds_read_b128 v[188:191], v155 offset:33792
	global_load_lds_dwordx4 v130, s[20:21]
	ds_read_b128 v[192:195], v155 offset:34816
	ds_read_b128 v[196:199], v155 offset:35840
	ds_read_b128 v[200:203], v155 offset:36864
	ds_read_b128 v[204:207], v155 offset:37888
	ds_read_b128 v[208:211], v155 offset:38912
	ds_read_b128 v[212:215], v155 offset:39936
	s_waitcnt vmcnt(8)
	s_waitcnt lgkmcnt(0)
	s_barrier
	v_mfma_f32_16x16x32_bf16 v[124:127], v[144:147], v[184:187], v[124:127]
	v_mfma_f32_16x16x32_bf16 v[120:123], v[160:163], v[184:187], v[120:123]
	v_mfma_f32_16x16x32_bf16 v[116:119], v[144:147], v[192:195], v[116:119]
	v_mfma_f32_16x16x32_bf16 v[112:115], v[160:163], v[192:195], v[112:115]
	v_mfma_f32_16x16x32_bf16 v[108:111], v[144:147], v[200:203], v[108:111]
	v_mfma_f32_16x16x32_bf16 v[104:107], v[160:163], v[200:203], v[104:107]
	v_mfma_f32_16x16x32_bf16 v[100:103], v[144:147], v[208:211], v[100:103]
	v_mfma_f32_16x16x32_bf16 v[96:99], v[160:163], v[208:211], v[96:99]
	v_mfma_f32_16x16x32_bf16 v[124:127], v[156:159], v[188:191], v[124:127]
	v_mfma_f32_16x16x32_bf16 v[120:123], v[164:167], v[188:191], v[120:123]
	v_mfma_f32_16x16x32_bf16 v[116:119], v[156:159], v[196:199], v[116:119]
	v_mfma_f32_16x16x32_bf16 v[112:115], v[164:167], v[196:199], v[112:115]
	v_mfma_f32_16x16x32_bf16 v[108:111], v[156:159], v[204:207], v[108:111]
	v_mfma_f32_16x16x32_bf16 v[104:107], v[164:167], v[204:207], v[104:107]
	v_mfma_f32_16x16x32_bf16 v[100:103], v[156:159], v[212:215], v[100:103]
	v_mfma_f32_16x16x32_bf16 v[96:99], v[164:167], v[212:215], v[96:99]
	v_mfma_f32_16x16x32_bf16 v[68:71], v[168:171], v[184:187], v[68:71]
	v_mfma_f32_16x16x32_bf16 v[64:67], v[176:179], v[184:187], v[64:67]
	v_mfma_f32_16x16x32_bf16 v[52:55], v[168:171], v[192:195], v[52:55]
	v_mfma_f32_16x16x32_bf16 v[48:51], v[176:179], v[192:195], v[48:51]
	v_mfma_f32_16x16x32_bf16 v[44:47], v[168:171], v[200:203], v[44:47]
	v_mfma_f32_16x16x32_bf16 v[40:43], v[176:179], v[200:203], v[40:43]
	v_mfma_f32_16x16x32_bf16 v[36:39], v[168:171], v[208:211], v[36:39]
	v_mfma_f32_16x16x32_bf16 v[32:35], v[176:179], v[208:211], v[32:35]
	v_mfma_f32_16x16x32_bf16 v[68:71], v[172:175], v[188:191], v[68:71]
	v_mfma_f32_16x16x32_bf16 v[64:67], v[180:183], v[188:191], v[64:67]
	v_mfma_f32_16x16x32_bf16 v[52:55], v[172:175], v[196:199], v[52:55]
	v_mfma_f32_16x16x32_bf16 v[48:51], v[180:183], v[196:199], v[48:51]
	v_mfma_f32_16x16x32_bf16 v[44:47], v[172:175], v[204:207], v[44:47]
	v_mfma_f32_16x16x32_bf16 v[40:43], v[180:183], v[204:207], v[40:43]
	v_mfma_f32_16x16x32_bf16 v[36:39], v[172:175], v[212:215], v[36:39]
	v_mfma_f32_16x16x32_bf16 v[32:35], v[180:183], v[212:215], v[32:35]
	s_barrier
	s_add_i32 s20, s24, s94
	s_add_u32 s98, s28, 0x80
	s_addc_u32 s99, s29, 0
	s_mov_b32 m0, s20
	ds_read_b128 v[184:187], v155 offset:49152
	global_load_lds_dwordx4 v132, s[98:99]
	s_add_i32 m0, s20, 0x2000
	s_add_u32 s20, s28, 0x160080
	s_addc_u32 s21, s29, 0
	s_add_i32 s24, s25, s94
	global_load_lds_dwordx4 v128, s[98:99]
	s_mov_b32 m0, s24
	ds_read_b128 v[188:191], v155 offset:50176
	global_load_lds_dwordx4 v132, s[20:21]
	s_add_i32 m0, s24, 0x2000
	ds_read_b128 v[192:195], v155 offset:51200
	global_load_lds_dwordx4 v128, s[20:21]
	s_add_u32 s100, s30, 0x80
	s_addc_u32 s101, s31, 0
	s_mov_b32 m0, s36
	ds_read_b128 v[196:199], v155 offset:52224
	global_load_lds_dwordx4 v134, s[100:101]
	s_mov_b32 m0, s37
	ds_read_b128 v[200:203], v155 offset:53248
	global_load_lds_dwordx4 v130, s[100:101]
	ds_read_b128 v[204:207], v155 offset:54272
	ds_read_b128 v[208:211], v155 offset:55296
	ds_read_b128 v[212:215], v155 offset:56320
	s_waitcnt vmcnt(8)
	s_waitcnt lgkmcnt(0)
	s_barrier
	v_mfma_f32_16x16x32_bf16 v[92:95], v[144:147], v[184:187], v[92:95]
	v_mfma_f32_16x16x32_bf16 v[88:91], v[160:163], v[184:187], v[88:91]
	v_mfma_f32_16x16x32_bf16 v[84:87], v[144:147], v[192:195], v[84:87]
	v_mfma_f32_16x16x32_bf16 v[80:83], v[160:163], v[192:195], v[80:83]
	v_mfma_f32_16x16x32_bf16 v[76:79], v[144:147], v[200:203], v[76:79]
	v_mfma_f32_16x16x32_bf16 v[72:75], v[160:163], v[200:203], v[72:75]
	v_mfma_f32_16x16x32_bf16 v[60:63], v[144:147], v[208:211], v[60:63]
	v_mfma_f32_16x16x32_bf16 v[56:59], v[160:163], v[208:211], v[56:59]
	v_mfma_f32_16x16x32_bf16 v[92:95], v[156:159], v[188:191], v[92:95]
	v_mfma_f32_16x16x32_bf16 v[88:91], v[164:167], v[188:191], v[88:91]
	v_mfma_f32_16x16x32_bf16 v[84:87], v[156:159], v[196:199], v[84:87]
	v_mfma_f32_16x16x32_bf16 v[80:83], v[164:167], v[196:199], v[80:83]
	v_mfma_f32_16x16x32_bf16 v[76:79], v[156:159], v[204:207], v[76:79]
	v_mfma_f32_16x16x32_bf16 v[72:75], v[164:167], v[204:207], v[72:75]
	v_mfma_f32_16x16x32_bf16 v[60:63], v[156:159], v[212:215], v[60:63]
	v_mfma_f32_16x16x32_bf16 v[56:59], v[164:167], v[212:215], v[56:59]
	v_mfma_f32_16x16x32_bf16 v[28:31], v[168:171], v[184:187], v[28:31]
	v_mfma_f32_16x16x32_bf16 v[24:27], v[176:179], v[184:187], v[24:27]
	v_mfma_f32_16x16x32_bf16 v[20:23], v[168:171], v[192:195], v[20:23]
	v_mfma_f32_16x16x32_bf16 v[16:19], v[176:179], v[192:195], v[16:19]
	v_mfma_f32_16x16x32_bf16 v[12:15], v[168:171], v[200:203], v[12:15]
	v_mfma_f32_16x16x32_bf16 v[8:11], v[176:179], v[200:203], v[8:11]
	v_mfma_f32_16x16x32_bf16 v[4:7], v[168:171], v[208:211], v[4:7]
	v_mfma_f32_16x16x32_bf16 v[0:3], v[176:179], v[208:211], v[0:3]
	v_mfma_f32_16x16x32_bf16 v[28:31], v[172:175], v[188:191], v[28:31]
	v_mfma_f32_16x16x32_bf16 v[24:27], v[180:183], v[188:191], v[24:27]
	v_mfma_f32_16x16x32_bf16 v[20:23], v[172:175], v[196:199], v[20:23]
	v_mfma_f32_16x16x32_bf16 v[16:19], v[180:183], v[196:199], v[16:19]
	v_mfma_f32_16x16x32_bf16 v[12:15], v[172:175], v[204:207], v[12:15]
	v_mfma_f32_16x16x32_bf16 v[8:11], v[180:183], v[204:207], v[8:11]
	v_mfma_f32_16x16x32_bf16 v[4:7], v[172:175], v[212:215], v[4:7]
	v_mfma_f32_16x16x32_bf16 v[0:3], v[180:183], v[212:215], v[0:3]
	s_barrier
	s_add_i32 s45, s45, 2
	s_add_u32 s43, s43, 0x100
	s_addc_u32 s44, s44, 0
	s_cmpk_gt_u32 s45, 0x55
	s_mov_b64 s[20:21], s[26:27]
	s_cbranch_scc0 .LBB0_1810
	s_and_b64 vcc, exec, s[22:23]
	s_cbranch_vccz .LBB0_1813
	s_barrier
